# code placement: the four GEMM K-loop heads my earlier edits had left at byte phase 4 mod 8 padded back to 0 mod 8 as in the baseline object (one s_nop before the head, one after the loop exit so all o
# speedup vs baseline: 1.0042x; 1.0042x over previous
; #define PG8_STAGE(bufoff, gbase, voff) do { _Pragma("unroll") for (int _i = 0; _i < 2; ++_i) \
;         __builtin_amdgcn_global_load_lds((const unsigned*)((const char*)(gbase) + (voff)[_i]), (PG8_LAS unsigned*)(lds + (bufoff) + ldsw + _i * 8192), 16, 0, 0); } while (0)
; #define PG8_LDA(dst, b, h) do { _Pragma("unroll") for (int m = 0; m < 4; ++m) _Pragma("unroll") for (int k = 0; k < 2; ++k) dst[m][k] = *(const PG8_LAS bf16x8*)(lds + PG8_SA(b, h) + aoff + m * 2048 + k * 1024); } while (0)
; #define PG8_LDB(dst, b, h) do { _Pragma("unroll") for (int n = 0; n < 2; ++n) _Pragma("unroll") for (int k = 0; k < 2; ++k) dst[n][k] = *(const PG8_LAS bf16x8*)(lds + PG8_SB(b, h) + boff + n * 2048 + k * 1024); } while (0)
; #define PG8_WAIT_V(n) asm volatile("s_waitcnt vmcnt(" #n ")" ::: "memory")
; #define PG8_WAIT_L(n) asm volatile("s_waitcnt lgkmcnt(" #n ")" ::: "memory")
; #define PG8_BAR __builtin_amdgcn_s_barrier()
; #define PG8_SCHED __builtin_amdgcn_sched_barrier(0)
; template <class Epi, class Sched, bool ALIGN_EPI = false, bool SP2 = false, bool AROWS128 = false>
; __device__ __forceinline__ void gemm_phase(PG8_LAS unsigned char* lds, const Gemm g, const Sched& S, const Epi& E) {
;     ...
;         const char* nA = has_next ? (const char*)g.A + (size_t)nxt.pm * tstep : cA; const char* nB = has_next ? (const char*)g.Bt + (size_t)nxt.pn * tstep : cB;
;         for (int t = 0; t < nt; t += 2) {
;             const bool last = (t == nt - 2);
;             const char* a1 = cA + (size_t)(t + 1) * kstep;
;             const char* a2 = last ? nA : cA + (size_t)(t + 2) * kstep; const char* b2 = last ? nB : cB + (size_t)(t + 2) * kstep;
;             const char* a3 = a2 + kstep; const char* b3 = b2 + kstep;
;             if (last && has_next) S.a_ready(nxt);
;             if constexpr (SP2) {
;             PG8_LDB(B0, 0, 0); PG8_LDB(B1, 0, 1); PG8_SCHED; PG8_LDA(At, 0, 0); PG8_STAGE(PG8_SA(1, 1), a1 + hstepA, voffA);
;             PG8_WAIT_V(8); PG8_WAIT_L(0); PG8_BAR; PG8_MMA(0, 0, At, B0); PG8_MMA(0, 1, At, B1); PG8_BAR; PG8_SCHED;
;     ...
; #pragma unroll
;         for (int a = 0; a < 2; ++a)
; #pragma unroll
;             for (int b = 0; b < 2; ++b)
; #pragma unroll
;                 for (int m = 0; m < 4; ++m)
; #pragma unroll
;                     for (int n = 0; n < 2; ++n) acc[a][b][m][n] = (f32x4){0.f, 0.f, 0.f, 0.f};
.LBB0_118:
	s_ashr_i32 s25, s24, 31
	s_lshl_b64 s[26:27], s[24:25], 19
	s_add_u32 s26, s46, s26
	s_addc_u32 s27, s47, s27
	s_and_b64 s[28:29], s[0:1], exec
	s_cselect_b32 s25, s27, s49
	s_cselect_b32 s76, s26, s48
	s_ashr_i32 s15, s14, 31
	s_lshl_b64 s[28:29], s[14:15], 19
	s_add_u32 s28, s82, s28
	s_addc_u32 s29, s83, s29
	s_and_b64 s[58:59], s[0:1], exec
	s_cselect_b32 s15, s29, s51
	s_cselect_b32 s77, s28, s50
	s_add_u32 s48, s48, 0x40080
	s_addc_u32 s49, s49, 0
	s_add_u32 s91, s50, 0x100
	v_mov_b32_e32 v0, 0
	s_addc_u32 s92, s51, 0
	s_mov_b32 s93, -2
	v_mov_b64_e32 v[0:1], 0
	v_mov_b64_e32 v[2:3], 0
	v_mov_b64_e32 v[4:5], 0
	v_mov_b64_e32 v[6:7], 0
	v_mov_b64_e32 v[8:9], 0
	v_mov_b64_e32 v[10:11], 0
	v_mov_b64_e32 v[12:13], 0
	v_mov_b64_e32 v[14:15], 0
	v_mov_b64_e32 v[16:17], 0
	v_mov_b64_e32 v[18:19], 0
	v_mov_b64_e32 v[20:21], 0
	v_mov_b64_e32 v[22:23], 0
	v_mov_b64_e32 v[24:25], 0
	v_mov_b64_e32 v[26:27], 0
	v_mov_b64_e32 v[28:29], 0
	v_mov_b64_e32 v[30:31], 0
	v_mov_b64_e32 v[32:33], 0
	v_mov_b64_e32 v[34:35], 0
	v_mov_b64_e32 v[36:37], 0
	v_mov_b64_e32 v[38:39], 0
	v_mov_b64_e32 v[40:41], 0
	v_mov_b64_e32 v[42:43], 0
	v_mov_b64_e32 v[44:45], 0
	v_mov_b64_e32 v[46:47], 0
	v_mov_b64_e32 v[48:49], 0
	v_mov_b64_e32 v[50:51], 0
	v_mov_b64_e32 v[52:53], 0
	v_mov_b64_e32 v[54:55], 0
	v_mov_b64_e32 v[56:57], 0
	v_mov_b64_e32 v[58:59], 0
	v_mov_b64_e32 v[60:61], 0
	v_mov_b64_e32 v[62:63], 0
	v_mov_b64_e32 v[64:65], 0
	v_mov_b64_e32 v[66:67], 0
	v_mov_b64_e32 v[68:69], 0
	v_mov_b64_e32 v[70:71], 0
	v_mov_b64_e32 v[72:73], 0
	v_mov_b64_e32 v[74:75], 0
	v_mov_b64_e32 v[76:77], 0
	v_mov_b64_e32 v[78:79], 0
	v_mov_b64_e32 v[80:81], 0
	v_mov_b64_e32 v[82:83], 0
	v_mov_b64_e32 v[84:85], 0
	v_mov_b64_e32 v[86:87], 0
	v_mov_b64_e32 v[88:89], 0
	v_mov_b64_e32 v[90:91], 0
	v_mov_b64_e32 v[92:93], 0
	v_mov_b64_e32 v[94:95], 0
	v_mov_b64_e32 v[96:97], 0
	v_mov_b64_e32 v[98:99], 0
	v_mov_b64_e32 v[100:101], 0
	v_mov_b64_e32 v[102:103], 0
	v_mov_b64_e32 v[104:105], 0
	v_mov_b64_e32 v[106:107], 0
	v_mov_b64_e32 v[108:109], 0
	v_mov_b64_e32 v[110:111], 0
	v_mov_b64_e32 v[112:113], 0
	v_mov_b64_e32 v[114:115], 0
	v_mov_b64_e32 v[116:117], 0
	v_mov_b64_e32 v[118:119], 0
	v_mov_b64_e32 v[120:121], 0
	v_mov_b64_e32 v[122:123], 0
	v_mov_b64_e32 v[124:125], 0
	v_mov_b64_e32 v[126:127], 0
	s_nop 0
.LBB0_119:
	ds_read_b128 v[148:151], v155
	ds_read_b128 v[160:163], v155 offset:1024
	ds_read_b128 v[164:167], v155 offset:2048
	ds_read_b128 v[168:171], v155 offset:3072
	ds_read_b128 v[172:175], v156
	ds_read_b128 v[176:179], v156 offset:1024
	ds_read_b128 v[180:183], v156 offset:2048
	ds_read_b128 v[184:187], v156 offset:3072
	s_add_u32 s50, s48, 0xfffc0080
	s_addc_u32 s51, s49, -1
	s_cmp_eq_u32 s93, 12
	s_cselect_b32 s59, s25, s51
	s_cselect_b32 s58, s76, s50
	s_cselect_b32 s51, s15, s92
	s_cselect_b32 s50, s77, s91
	v_lshl_add_u64 v[208:209], s[48:49], 0, v[138:139]
	s_add_i32 m0, s31, 0xc000
	ds_read_b128 v[188:191], v157
	ds_read_b128 v[192:195], v157 offset:1024
	ds_read_b128 v[196:199], v157 offset:2048
	ds_read_b128 v[200:203], v157 offset:3072
	ds_read_b128 v[204:207], v157 offset:4096
	ds_read_b128 v[212:215], v157 offset:5120
	ds_read_b128 v[216:219], v157 offset:6144
	ds_read_b128 v[220:223], v157 offset:7168
	global_load_lds_dwordx4 v[208:209], off
	v_lshl_add_u64 v[208:209], s[48:49], 0, v[140:141]
	s_add_i32 m0, s31, 0xe000
	s_nop 0
	global_load_lds_dwordx4 v[208:209], off
	s_waitcnt vmcnt(8)
	s_waitcnt lgkmcnt(0)
	s_barrier
	s_setprio 1
	s_waitcnt lgkmcnt(0)
	v_mfma_f32_16x16x32_bf16 v[124:127], v[148:151], v[188:191], v[124:127]
	v_mfma_f32_16x16x32_bf16 v[120:123], v[164:167], v[188:191], v[120:123]
	v_mfma_f32_16x16x32_bf16 v[112:115], v[148:151], v[196:199], v[112:115]
	v_mfma_f32_16x16x32_bf16 v[104:107], v[164:167], v[196:199], v[104:107]
	v_mfma_f32_16x16x32_bf16 v[96:99], v[148:151], v[204:207], v[96:99]
	v_mfma_f32_16x16x32_bf16 v[88:91], v[164:167], v[204:207], v[88:91]
	v_mfma_f32_16x16x32_bf16 v[80:83], v[148:151], v[216:219], v[80:83]
	v_mfma_f32_16x16x32_bf16 v[72:75], v[164:167], v[216:219], v[72:75]
	v_mfma_f32_16x16x32_bf16 v[124:127], v[160:163], v[192:195], v[124:127]
	v_mfma_f32_16x16x32_bf16 v[120:123], v[168:171], v[192:195], v[120:123]
	v_mfma_f32_16x16x32_bf16 v[112:115], v[160:163], v[200:203], v[112:115]
	v_mfma_f32_16x16x32_bf16 v[104:107], v[168:171], v[200:203], v[104:107]
	v_mfma_f32_16x16x32_bf16 v[96:99], v[160:163], v[212:215], v[96:99]
	v_mfma_f32_16x16x32_bf16 v[88:91], v[168:171], v[212:215], v[88:91]
	v_mfma_f32_16x16x32_bf16 v[80:83], v[160:163], v[220:223], v[80:83]
	v_mfma_f32_16x16x32_bf16 v[72:75], v[168:171], v[220:223], v[72:75]
	s_setprio 0
	s_setprio 1
	v_mfma_f32_16x16x32_bf16 v[116:119], v[172:175], v[188:191], v[116:119]
	v_mfma_f32_16x16x32_bf16 v[108:111], v[180:183], v[188:191], v[108:111]
	v_mfma_f32_16x16x32_bf16 v[100:103], v[172:175], v[196:199], v[100:103]
	v_mfma_f32_16x16x32_bf16 v[92:95], v[180:183], v[196:199], v[92:95]
	v_mfma_f32_16x16x32_bf16 v[84:87], v[172:175], v[204:207], v[84:87]
	v_mfma_f32_16x16x32_bf16 v[76:79], v[180:183], v[204:207], v[76:79]
	v_mfma_f32_16x16x32_bf16 v[68:71], v[172:175], v[216:219], v[68:71]
	v_mfma_f32_16x16x32_bf16 v[64:67], v[180:183], v[216:219], v[64:67]
	v_mfma_f32_16x16x32_bf16 v[116:119], v[176:179], v[192:195], v[116:119]
	v_mfma_f32_16x16x32_bf16 v[108:111], v[184:187], v[192:195], v[108:111]
	v_mfma_f32_16x16x32_bf16 v[100:103], v[176:179], v[200:203], v[100:103]
	v_mfma_f32_16x16x32_bf16 v[92:95], v[184:187], v[200:203], v[92:95]
	v_mfma_f32_16x16x32_bf16 v[84:87], v[176:179], v[212:215], v[84:87]
	v_mfma_f32_16x16x32_bf16 v[76:79], v[184:187], v[212:215], v[76:79]
	v_mfma_f32_16x16x32_bf16 v[68:71], v[176:179], v[220:223], v[68:71]
	v_mfma_f32_16x16x32_bf16 v[64:67], v[184:187], v[220:223], v[64:67]
	s_setprio 0
	s_barrier
; #define PG8_STAGE(bufoff, gbase, voff) do { _Pragma("unroll") for (int _i = 0; _i < 2; ++_i) \
;         __builtin_amdgcn_global_load_lds((const unsigned*)((const char*)(gbase) + (voff)[_i]), (PG8_LAS unsigned*)(lds + (bufoff) + ldsw + _i * 8192), 16, 0, 0); } while (0)
; #define PG8_LDA(dst, b, h) do { _Pragma("unroll") for (int m = 0; m < 4; ++m) _Pragma("unroll") for (int k = 0; k < 2; ++k) dst[m][k] = *(const PG8_LAS bf16x8*)(lds + PG8_SA(b, h) + aoff + m * 2048 + k * 1024); } while (0)
; #define PG8_LDB(dst, b, h) do { _Pragma("unroll") for (int n = 0; n < 2; ++n) _Pragma("unroll") for (int k = 0; k < 2; ++k) dst[n][k] = *(const PG8_LAS bf16x8*)(lds + PG8_SB(b, h) + boff + n * 2048 + k * 1024); } while (0)
; #define PG8_MMA(ai, bj, At, Bt) do { __builtin_amdgcn_s_setprio(1); _Pragma("unroll") for (int m = 0; m < 4; ++m) _Pragma("unroll") for (int n = 0; n < 2; ++n) _Pragma("unroll") for (int k = 0; k < 2; ++k) \
;         acc[ai][bj][m][n] = __builtin_amdgcn_mfma_f32_16x16x32_bf16(Bt[n][k], At[m][k], acc[ai][bj][m][n], 0, 0, 0); __builtin_amdgcn_s_setprio(0); } while (0)
; #define PG8_WAIT_V(n) asm volatile("s_waitcnt vmcnt(" #n ")" ::: "memory")
; #define PG8_WAIT_L(n) asm volatile("s_waitcnt lgkmcnt(" #n ")" ::: "memory")
; #define PG8_BAR __builtin_amdgcn_s_barrier()
; #define PG8_SCHED __builtin_amdgcn_sched_barrier(0)
; template <class Epi, class Sched, bool ALIGN_EPI = false, bool SP2 = false, bool AROWS128 = false>
; __device__ __forceinline__ void gemm_phase(PG8_LAS unsigned char* lds, const Gemm g, const Sched& S, const Epi& E) {
;     ...
;             PG8_LDA(At, 0, 1); PG8_STAGE(PG8_SB(0, 0), b2, voffB); PG8_STAGE(PG8_SB(0, 1), b2 + hstep, voffB); PG8_STAGE(PG8_SA(0, 0), a2, voffA);
;             PG8_WAIT_V(8); PG8_WAIT_L(0); PG8_BAR; PG8_MMA(1, 0, At, B0); PG8_MMA(1, 1, At, B1); PG8_BAR; PG8_SCHED;
;             PG8_LDB(B0, 1, 0); PG8_LDB(B1, 1, 1); PG8_SCHED; PG8_LDA(At, 1, 0); PG8_STAGE(PG8_SA(0, 1), a2 + hstepA, voffA);
;             PG8_WAIT_V(8); PG8_WAIT_L(0); PG8_BAR; PG8_MMA(0, 0, At, B0); PG8_MMA(0, 1, At, B1); PG8_BAR; PG8_SCHED;
	s_add_i32 s94, s87, s3
	v_lshl_add_u64 v[208:209], s[50:51], 0, v[134:135]
	s_mov_b32 m0, s94
	ds_read_b128 v[188:191], v157 offset:16384
	ds_read_b128 v[192:195], v157 offset:17408
	ds_read_b128 v[196:199], v157 offset:18432
	ds_read_b128 v[200:203], v157 offset:19456
	ds_read_b128 v[204:207], v157 offset:20480
	ds_read_b128 v[212:215], v157 offset:21504
	ds_read_b128 v[216:219], v157 offset:22528
	ds_read_b128 v[220:223], v157 offset:23552
	global_load_lds_dwordx4 v[208:209], off
	s_add_i32 m0, s94, 0x2000
	s_add_u32 s94, s50, 0x40000
	v_lshl_add_u64 v[224:225], s[50:51], 0, v[130:131]
	s_addc_u32 s95, s51, 0
	s_add_i32 s96, s88, s3
	global_load_lds_dwordx4 v[224:225], off
	v_lshl_add_u64 v[226:227], s[94:95], 0, v[134:135]
	s_mov_b32 m0, s96
	v_lshl_add_u64 v[228:229], s[58:59], 0, v[132:133]
	global_load_lds_dwordx4 v[226:227], off
	v_lshl_add_u64 v[226:227], s[94:95], 0, v[130:131]
	s_add_i32 m0, s96, 0x2000
	s_nop 0
	global_load_lds_dwordx4 v[226:227], off
	v_lshl_add_u64 v[226:227], s[58:59], 0, v[136:137]
	s_mov_b32 m0, s31
	s_nop 0
	global_load_lds_dwordx4 v[226:227], off
	s_mov_b32 m0, s64
	s_nop 0
	global_load_lds_dwordx4 v[228:229], off
	s_waitcnt vmcnt(8)
	s_waitcnt lgkmcnt(0)
	s_barrier
	s_setprio 1
	s_waitcnt lgkmcnt(0)
	v_mfma_f32_16x16x32_bf16 v[60:63], v[148:151], v[188:191], v[60:63]
	v_mfma_f32_16x16x32_bf16 v[56:59], v[164:167], v[188:191], v[56:59]
	v_mfma_f32_16x16x32_bf16 v[48:51], v[148:151], v[196:199], v[48:51]
	v_mfma_f32_16x16x32_bf16 v[40:43], v[164:167], v[196:199], v[40:43]
	v_mfma_f32_16x16x32_bf16 v[32:35], v[148:151], v[204:207], v[32:35]
	v_mfma_f32_16x16x32_bf16 v[24:27], v[164:167], v[204:207], v[24:27]
	v_mfma_f32_16x16x32_bf16 v[16:19], v[148:151], v[216:219], v[16:19]
	v_mfma_f32_16x16x32_bf16 v[8:11], v[164:167], v[216:219], v[8:11]
	v_mfma_f32_16x16x32_bf16 v[60:63], v[160:163], v[192:195], v[60:63]
	v_mfma_f32_16x16x32_bf16 v[56:59], v[168:171], v[192:195], v[56:59]
	v_mfma_f32_16x16x32_bf16 v[48:51], v[160:163], v[200:203], v[48:51]
	v_mfma_f32_16x16x32_bf16 v[40:43], v[168:171], v[200:203], v[40:43]
	v_mfma_f32_16x16x32_bf16 v[32:35], v[160:163], v[212:215], v[32:35]
	v_mfma_f32_16x16x32_bf16 v[24:27], v[168:171], v[212:215], v[24:27]
	v_mfma_f32_16x16x32_bf16 v[16:19], v[160:163], v[220:223], v[16:19]
	v_mfma_f32_16x16x32_bf16 v[8:11], v[168:171], v[220:223], v[8:11]
	s_setprio 0
	s_setprio 1
	v_mfma_f32_16x16x32_bf16 v[52:55], v[172:175], v[188:191], v[52:55]
	v_mfma_f32_16x16x32_bf16 v[44:47], v[180:183], v[188:191], v[44:47]
	v_mfma_f32_16x16x32_bf16 v[36:39], v[172:175], v[196:199], v[36:39]
	v_mfma_f32_16x16x32_bf16 v[28:31], v[180:183], v[196:199], v[28:31]
	v_mfma_f32_16x16x32_bf16 v[20:23], v[172:175], v[204:207], v[20:23]
	v_mfma_f32_16x16x32_bf16 v[12:15], v[180:183], v[204:207], v[12:15]
	v_mfma_f32_16x16x32_bf16 v[4:7], v[172:175], v[216:219], v[4:7]
	v_mfma_f32_16x16x32_bf16 v[0:3], v[180:183], v[216:219], v[0:3]
	v_mfma_f32_16x16x32_bf16 v[52:55], v[176:179], v[192:195], v[52:55]
	v_mfma_f32_16x16x32_bf16 v[44:47], v[184:187], v[192:195], v[44:47]
	v_mfma_f32_16x16x32_bf16 v[36:39], v[176:179], v[200:203], v[36:39]
	v_mfma_f32_16x16x32_bf16 v[28:31], v[184:187], v[200:203], v[28:31]
	v_mfma_f32_16x16x32_bf16 v[20:23], v[176:179], v[212:215], v[20:23]
	v_mfma_f32_16x16x32_bf16 v[12:15], v[184:187], v[212:215], v[12:15]
	v_mfma_f32_16x16x32_bf16 v[4:7], v[176:179], v[220:223], v[4:7]
	v_mfma_f32_16x16x32_bf16 v[0:3], v[184:187], v[220:223], v[0:3]
	s_setprio 0
	s_barrier
	s_add_i32 s94, 0, 0x18000
	v_add_u32_e32 v146, s94, v153
	s_add_i32 s95, 0, 0x1c000
	ds_read_b128 v[148:151], v146
	ds_read_b128 v[160:163], v146 offset:1024
	ds_read_b128 v[164:167], v146 offset:2048
	ds_read_b128 v[168:171], v146 offset:3072
	v_add_u32_e32 v146, s95, v153
	ds_read_b128 v[172:175], v146
	ds_read_b128 v[176:179], v146 offset:1024
	ds_read_b128 v[180:183], v146 offset:2048
	ds_read_b128 v[184:187], v146 offset:3072
	s_add_u32 s58, s58, 0x40000
	s_addc_u32 s59, s59, 0
	s_mov_b32 m0, s65
	v_lshl_add_u64 v[230:231], s[58:59], 0, v[136:137]
	ds_read_b128 v[188:191], v157 offset:32768
	ds_read_b128 v[192:195], v157 offset:33792
	ds_read_b128 v[196:199], v157 offset:34816
	ds_read_b128 v[200:203], v157 offset:35840
	ds_read_b128 v[204:207], v157 offset:36864
	ds_read_b128 v[212:215], v157 offset:37888
	ds_read_b128 v[216:219], v157 offset:38912
	ds_read_b128 v[220:223], v157 offset:39936
	global_load_lds_dwordx4 v[230:231], off
	v_lshl_add_u64 v[230:231], s[58:59], 0, v[132:133]
	s_mov_b32 m0, s72
	s_nop 0
	global_load_lds_dwordx4 v[230:231], off
	s_waitcnt vmcnt(8)
	s_waitcnt lgkmcnt(0)
	s_barrier
; #define PG8_STAGE(bufoff, gbase, voff) do { _Pragma("unroll") for (int _i = 0; _i < 2; ++_i) \
;         __builtin_amdgcn_global_load_lds((const unsigned*)((const char*)(gbase) + (voff)[_i]), (PG8_LAS unsigned*)(lds + (bufoff) + ldsw + _i * 8192), 16, 0, 0); } while (0)
; #define PG8_LDA(dst, b, h) do { _Pragma("unroll") for (int m = 0; m < 4; ++m) _Pragma("unroll") for (int k = 0; k < 2; ++k) dst[m][k] = *(const PG8_LAS bf16x8*)(lds + PG8_SA(b, h) + aoff + m * 2048 + k * 1024); } while (0)
; #define PG8_MMA(ai, bj, At, Bt) do { __builtin_amdgcn_s_setprio(1); _Pragma("unroll") for (int m = 0; m < 4; ++m) _Pragma("unroll") for (int n = 0; n < 2; ++n) _Pragma("unroll") for (int k = 0; k < 2; ++k) \
;         acc[ai][bj][m][n] = __builtin_amdgcn_mfma_f32_16x16x32_bf16(Bt[n][k], At[m][k], acc[ai][bj][m][n], 0, 0, 0); __builtin_amdgcn_s_setprio(0); } while (0)
; #define PG8_WAIT_V(n) asm volatile("s_waitcnt vmcnt(" #n ")" ::: "memory")
; #define PG8_WAIT_L(n) asm volatile("s_waitcnt lgkmcnt(" #n ")" ::: "memory")
; #define PG8_BAR __builtin_amdgcn_s_barrier()
; #define PG8_SCHED __builtin_amdgcn_sched_barrier(0)
; template <class Epi, class Sched, bool ALIGN_EPI = false, bool SP2 = false, bool AROWS128 = false>
; __device__ __forceinline__ void gemm_phase(PG8_LAS unsigned char* lds, const Gemm g, const Sched& S, const Epi& E) {
;     ...
;         for (int t = 0; t < nt; t += 2) {
;     ...
;             PG8_WAIT_V(8); PG8_WAIT_L(0); PG8_BAR; PG8_MMA(0, 0, At, B0); PG8_MMA(0, 1, At, B1); PG8_BAR; PG8_SCHED;
;             PG8_LDA(At, 1, 1); PG8_STAGE(PG8_SB(1, 0), b3, voffB); PG8_STAGE(PG8_SB(1, 1), b3 + hstep, voffB); PG8_STAGE(PG8_SA(1, 0), a3, voffA);
;             PG8_WAIT_V(8); PG8_WAIT_L(0); PG8_BAR; PG8_MMA(1, 0, At, B0); PG8_MMA(1, 1, At, B1); PG8_BAR; PG8_SCHED;
	s_setprio 1
	s_waitcnt lgkmcnt(0)
	v_mfma_f32_16x16x32_bf16 v[124:127], v[148:151], v[188:191], v[124:127]
	v_mfma_f32_16x16x32_bf16 v[120:123], v[164:167], v[188:191], v[120:123]
	v_mfma_f32_16x16x32_bf16 v[112:115], v[148:151], v[196:199], v[112:115]
	v_mfma_f32_16x16x32_bf16 v[104:107], v[164:167], v[196:199], v[104:107]
	v_mfma_f32_16x16x32_bf16 v[96:99], v[148:151], v[204:207], v[96:99]
	v_mfma_f32_16x16x32_bf16 v[88:91], v[164:167], v[204:207], v[88:91]
	v_mfma_f32_16x16x32_bf16 v[80:83], v[148:151], v[216:219], v[80:83]
	v_mfma_f32_16x16x32_bf16 v[72:75], v[164:167], v[216:219], v[72:75]
	v_mfma_f32_16x16x32_bf16 v[124:127], v[160:163], v[192:195], v[124:127]
	v_mfma_f32_16x16x32_bf16 v[120:123], v[168:171], v[192:195], v[120:123]
	v_mfma_f32_16x16x32_bf16 v[112:115], v[160:163], v[200:203], v[112:115]
	v_mfma_f32_16x16x32_bf16 v[104:107], v[168:171], v[200:203], v[104:107]
	v_mfma_f32_16x16x32_bf16 v[96:99], v[160:163], v[212:215], v[96:99]
	v_mfma_f32_16x16x32_bf16 v[88:91], v[168:171], v[212:215], v[88:91]
	v_mfma_f32_16x16x32_bf16 v[80:83], v[160:163], v[220:223], v[80:83]
	v_mfma_f32_16x16x32_bf16 v[72:75], v[168:171], v[220:223], v[72:75]
	s_setprio 0
	s_setprio 1
	v_mfma_f32_16x16x32_bf16 v[116:119], v[172:175], v[188:191], v[116:119]
	v_mfma_f32_16x16x32_bf16 v[108:111], v[180:183], v[188:191], v[108:111]
	v_mfma_f32_16x16x32_bf16 v[100:103], v[172:175], v[196:199], v[100:103]
	v_mfma_f32_16x16x32_bf16 v[92:95], v[180:183], v[196:199], v[92:95]
	v_mfma_f32_16x16x32_bf16 v[84:87], v[172:175], v[204:207], v[84:87]
	v_mfma_f32_16x16x32_bf16 v[76:79], v[180:183], v[204:207], v[76:79]
	v_mfma_f32_16x16x32_bf16 v[68:71], v[172:175], v[216:219], v[68:71]
	v_mfma_f32_16x16x32_bf16 v[64:67], v[180:183], v[216:219], v[64:67]
	v_mfma_f32_16x16x32_bf16 v[116:119], v[176:179], v[192:195], v[116:119]
	v_mfma_f32_16x16x32_bf16 v[108:111], v[184:187], v[192:195], v[108:111]
	v_mfma_f32_16x16x32_bf16 v[100:103], v[176:179], v[200:203], v[100:103]
	v_mfma_f32_16x16x32_bf16 v[92:95], v[184:187], v[200:203], v[92:95]
	v_mfma_f32_16x16x32_bf16 v[84:87], v[176:179], v[212:215], v[84:87]
	v_mfma_f32_16x16x32_bf16 v[76:79], v[184:187], v[212:215], v[76:79]
	v_mfma_f32_16x16x32_bf16 v[68:71], v[176:179], v[220:223], v[68:71]
	v_mfma_f32_16x16x32_bf16 v[64:67], v[184:187], v[220:223], v[64:67]
	s_setprio 0
	s_barrier
	s_add_i32 s58, s94, s3
	v_lshl_add_u64 v[208:209], v[208:209], 0, s[6:7]
	s_mov_b32 m0, s58
	ds_read_b128 v[188:191], v157 offset:49152
	ds_read_b128 v[192:195], v157 offset:50176
	ds_read_b128 v[196:199], v157 offset:51200
	ds_read_b128 v[200:203], v157 offset:52224
	ds_read_b128 v[204:207], v157 offset:53248
	ds_read_b128 v[212:215], v157 offset:54272
	ds_read_b128 v[216:219], v157 offset:55296
	ds_read_b128 v[220:223], v157 offset:56320
	global_load_lds_dwordx4 v[208:209], off
	s_add_i32 m0, s58, 0x2000
	s_add_u32 s50, s50, 0x40080
	v_lshl_add_u64 v[208:209], v[224:225], 0, s[6:7]
	s_addc_u32 s51, s51, 0
	s_add_i32 s58, s95, s3
	global_load_lds_dwordx4 v[208:209], off
	v_lshl_add_u64 v[208:209], s[50:51], 0, v[134:135]
	s_mov_b32 m0, s58
	s_nop 0
	global_load_lds_dwordx4 v[208:209], off
	v_lshl_add_u64 v[208:209], s[50:51], 0, v[130:131]
	s_add_i32 m0, s58, 0x2000
	s_nop 0
	global_load_lds_dwordx4 v[208:209], off
	v_lshl_add_u64 v[208:209], v[226:227], 0, s[6:7]
	s_mov_b32 m0, s81
	s_nop 0
	global_load_lds_dwordx4 v[208:209], off
	v_lshl_add_u64 v[208:209], v[228:229], 0, s[6:7]
	s_mov_b32 m0, s84
	s_nop 0
	global_load_lds_dwordx4 v[208:209], off
	s_waitcnt vmcnt(8)
	s_waitcnt lgkmcnt(0)
	s_barrier
	s_setprio 1
	s_waitcnt lgkmcnt(0)
	v_mfma_f32_16x16x32_bf16 v[60:63], v[148:151], v[188:191], v[60:63]
	v_mfma_f32_16x16x32_bf16 v[56:59], v[164:167], v[188:191], v[56:59]
	v_mfma_f32_16x16x32_bf16 v[48:51], v[148:151], v[196:199], v[48:51]
	v_mfma_f32_16x16x32_bf16 v[40:43], v[164:167], v[196:199], v[40:43]
	v_mfma_f32_16x16x32_bf16 v[32:35], v[148:151], v[204:207], v[32:35]
	v_mfma_f32_16x16x32_bf16 v[24:27], v[164:167], v[204:207], v[24:27]
	v_mfma_f32_16x16x32_bf16 v[16:19], v[148:151], v[216:219], v[16:19]
	v_mfma_f32_16x16x32_bf16 v[8:11], v[164:167], v[216:219], v[8:11]
	v_mfma_f32_16x16x32_bf16 v[60:63], v[160:163], v[192:195], v[60:63]
	v_mfma_f32_16x16x32_bf16 v[56:59], v[168:171], v[192:195], v[56:59]
	v_mfma_f32_16x16x32_bf16 v[48:51], v[160:163], v[200:203], v[48:51]
	v_mfma_f32_16x16x32_bf16 v[40:43], v[168:171], v[200:203], v[40:43]
	v_mfma_f32_16x16x32_bf16 v[32:35], v[160:163], v[212:215], v[32:35]
	v_mfma_f32_16x16x32_bf16 v[24:27], v[168:171], v[212:215], v[24:27]
	v_mfma_f32_16x16x32_bf16 v[16:19], v[160:163], v[220:223], v[16:19]
	v_mfma_f32_16x16x32_bf16 v[8:11], v[168:171], v[220:223], v[8:11]
	s_setprio 0
	s_setprio 1
	v_mfma_f32_16x16x32_bf16 v[52:55], v[172:175], v[188:191], v[52:55]
	v_mfma_f32_16x16x32_bf16 v[44:47], v[180:183], v[188:191], v[44:47]
	v_mfma_f32_16x16x32_bf16 v[36:39], v[172:175], v[196:199], v[36:39]
	v_mfma_f32_16x16x32_bf16 v[28:31], v[180:183], v[196:199], v[28:31]
	v_mfma_f32_16x16x32_bf16 v[20:23], v[172:175], v[204:207], v[20:23]
	v_mfma_f32_16x16x32_bf16 v[12:15], v[180:183], v[204:207], v[12:15]
	v_mfma_f32_16x16x32_bf16 v[4:7], v[172:175], v[216:219], v[4:7]
	v_mfma_f32_16x16x32_bf16 v[0:3], v[180:183], v[216:219], v[0:3]
	v_mfma_f32_16x16x32_bf16 v[52:55], v[176:179], v[192:195], v[52:55]
	v_mfma_f32_16x16x32_bf16 v[44:47], v[184:187], v[192:195], v[44:47]
	v_mfma_f32_16x16x32_bf16 v[36:39], v[176:179], v[200:203], v[36:39]
	v_mfma_f32_16x16x32_bf16 v[28:31], v[184:187], v[200:203], v[28:31]
	v_mfma_f32_16x16x32_bf16 v[20:23], v[176:179], v[212:215], v[20:23]
	v_mfma_f32_16x16x32_bf16 v[12:15], v[184:187], v[212:215], v[12:15]
	v_mfma_f32_16x16x32_bf16 v[4:7], v[176:179], v[220:223], v[4:7]
	v_mfma_f32_16x16x32_bf16 v[0:3], v[184:187], v[220:223], v[0:3]
	s_setprio 0
	s_barrier
	s_add_i32 s93, s93, 2
	s_add_u32 s48, s48, 0x100
	s_addc_u32 s49, s49, 0
	s_add_u32 s91, s91, 0x100
	s_addc_u32 s92, s92, 0
	s_cmp_gt_u32 s93, 13
	s_cbranch_scc0 .LBB0_119
	s_nop 0
	s_and_b64 vcc, exec, s[10:11]
	s_cbranch_vccz .LBB0_122
	s_barrier

; #define PG8_STAGE(bufoff, gbase, voff) do { _Pragma("unroll") for (int _i = 0; _i < 2; ++_i) \
;         __builtin_amdgcn_global_load_lds((const unsigned*)((const char*)(gbase) + (voff)[_i]), (PG8_LAS unsigned*)(lds + (bufoff) + ldsw + _i * 8192), 16, 0, 0); } while (0)
; #define PG8_LDA(dst, b, h) do { _Pragma("unroll") for (int m = 0; m < 4; ++m) _Pragma("unroll") for (int k = 0; k < 2; ++k) dst[m][k] = *(const PG8_LAS bf16x8*)(lds + PG8_SA(b, h) + aoff + m * 2048 + k * 1024); } while (0)
; #define PG8_LDB(dst, b, h) do { _Pragma("unroll") for (int n = 0; n < 2; ++n) _Pragma("unroll") for (int k = 0; k < 2; ++k) dst[n][k] = *(const PG8_LAS bf16x8*)(lds + PG8_SB(b, h) + boff + n * 2048 + k * 1024); } while (0)
; #define PG8_WAIT_V(n) asm volatile("s_waitcnt vmcnt(" #n ")" ::: "memory")
; #define PG8_WAIT_L(n) asm volatile("s_waitcnt lgkmcnt(" #n ")" ::: "memory")
; #define PG8_BAR __builtin_amdgcn_s_barrier()
; #define PG8_SCHED __builtin_amdgcn_sched_barrier(0)
; template <class Epi, class Sched, bool ALIGN_EPI = false, bool SP2 = false, bool AROWS128 = false>
; __device__ __forceinline__ void gemm_phase(PG8_LAS unsigned char* lds, const Gemm g, const Sched& S, const Epi& E) {
;     ...
;         const char* nA = has_next ? (const char*)g.A + (size_t)nxt.pm * tstep : cA; const char* nB = has_next ? (const char*)g.Bt + (size_t)nxt.pn * tstep : cB;
;         for (int t = 0; t < nt; t += 2) {
;             const bool last = (t == nt - 2);
;             const char* a1 = cA + (size_t)(t + 1) * kstep;
;             const char* a2 = last ? nA : cA + (size_t)(t + 2) * kstep; const char* b2 = last ? nB : cB + (size_t)(t + 2) * kstep;
;             const char* a3 = a2 + kstep; const char* b3 = b2 + kstep;
;             if (last && has_next) S.a_ready(nxt);
;             if constexpr (SP2) {
;             PG8_LDB(B0, 0, 0); PG8_LDB(B1, 0, 1); PG8_SCHED; PG8_LDA(At, 0, 0); PG8_STAGE(PG8_SA(1, 1), a1 + hstepA, voffA);
;             PG8_WAIT_V(8); PG8_WAIT_L(0); PG8_BAR; PG8_MMA(0, 0, At, B0); PG8_MMA(0, 1, At, B1); PG8_BAR; PG8_SCHED;
;     ...
; #pragma unroll
;         for (int a = 0; a < 2; ++a)
; #pragma unroll
;             for (int b = 0; b < 2; ++b)
; #pragma unroll
;                 for (int m = 0; m < 4; ++m)
; #pragma unroll
;                     for (int n = 0; n < 2; ++n) acc[a][b][m][n] = (f32x4){0.f, 0.f, 0.f, 0.f};
.LBB0_488:
	s_ashr_i32 s15, s14, 31
	s_lshl_b64 s[16:17], s[14:15], 19
	s_add_u32 s16, s46, s16
	s_addc_u32 s17, s47, s17
	s_and_b64 s[18:19], s[0:1], exec
	s_cselect_b32 s15, s17, s27
	s_cselect_b32 s76, s16, s26
	s_ashr_i32 s13, s12, 31
	s_lshl_b64 s[18:19], s[12:13], 19
	s_add_u32 s18, s20, s18
	s_addc_u32 s19, s21, s19
	s_and_b64 s[30:31], s[0:1], exec
	s_cselect_b32 s13, s19, s29
	s_cselect_b32 s77, s18, s28
	s_add_u32 s26, s26, 0x40080
	s_addc_u32 s27, s27, 0
	s_add_u32 s82, s28, 0x100
	v_mov_b32_e32 v0, 0
	s_addc_u32 s83, s29, 0
	s_mov_b32 s84, -2
	v_mov_b64_e32 v[0:1], 0
	v_mov_b64_e32 v[2:3], 0
	v_mov_b64_e32 v[4:5], 0
	v_mov_b64_e32 v[6:7], 0
	v_mov_b64_e32 v[8:9], 0
	v_mov_b64_e32 v[10:11], 0
	v_mov_b64_e32 v[12:13], 0
	v_mov_b64_e32 v[14:15], 0
	v_mov_b64_e32 v[16:17], 0
	v_mov_b64_e32 v[18:19], 0
	v_mov_b64_e32 v[20:21], 0
	v_mov_b64_e32 v[22:23], 0
	v_mov_b64_e32 v[24:25], 0
	v_mov_b64_e32 v[26:27], 0
	v_mov_b64_e32 v[28:29], 0
	v_mov_b64_e32 v[30:31], 0
	v_mov_b64_e32 v[32:33], 0
	v_mov_b64_e32 v[34:35], 0
	v_mov_b64_e32 v[36:37], 0
	v_mov_b64_e32 v[38:39], 0
	v_mov_b64_e32 v[40:41], 0
	v_mov_b64_e32 v[42:43], 0
	v_mov_b64_e32 v[44:45], 0
	v_mov_b64_e32 v[46:47], 0
	v_mov_b64_e32 v[48:49], 0
	v_mov_b64_e32 v[50:51], 0
	v_mov_b64_e32 v[52:53], 0
	v_mov_b64_e32 v[54:55], 0
	v_mov_b64_e32 v[56:57], 0
	v_mov_b64_e32 v[58:59], 0
	v_mov_b64_e32 v[60:61], 0
	v_mov_b64_e32 v[62:63], 0
	v_mov_b64_e32 v[64:65], 0
	v_mov_b64_e32 v[66:67], 0
	v_mov_b64_e32 v[68:69], 0
	v_mov_b64_e32 v[70:71], 0
	v_mov_b64_e32 v[72:73], 0
	v_mov_b64_e32 v[74:75], 0
	v_mov_b64_e32 v[76:77], 0
	v_mov_b64_e32 v[78:79], 0
	v_mov_b64_e32 v[80:81], 0
	v_mov_b64_e32 v[82:83], 0
	v_mov_b64_e32 v[84:85], 0
	v_mov_b64_e32 v[86:87], 0
	v_mov_b64_e32 v[88:89], 0
	v_mov_b64_e32 v[90:91], 0
	v_mov_b64_e32 v[92:93], 0
	v_mov_b64_e32 v[94:95], 0
	v_mov_b64_e32 v[96:97], 0
	v_mov_b64_e32 v[98:99], 0
	v_mov_b64_e32 v[100:101], 0
	v_mov_b64_e32 v[102:103], 0
	v_mov_b64_e32 v[104:105], 0
	v_mov_b64_e32 v[106:107], 0
	v_mov_b64_e32 v[108:109], 0
	v_mov_b64_e32 v[110:111], 0
	v_mov_b64_e32 v[112:113], 0
	v_mov_b64_e32 v[114:115], 0
	v_mov_b64_e32 v[116:117], 0
	v_mov_b64_e32 v[118:119], 0
	v_mov_b64_e32 v[120:121], 0
	v_mov_b64_e32 v[122:123], 0
	v_mov_b64_e32 v[124:125], 0
	v_mov_b64_e32 v[126:127], 0
	s_nop 0
.LBB0_489:
	ds_read_b128 v[152:155], v149
	ds_read_b128 v[156:159], v149 offset:1024
	ds_read_b128 v[160:163], v149 offset:2048
	ds_read_b128 v[164:167], v149 offset:3072
	ds_read_b128 v[168:171], v150
	ds_read_b128 v[172:175], v150 offset:1024
	ds_read_b128 v[176:179], v150 offset:2048
	ds_read_b128 v[180:183], v150 offset:3072
	s_add_u32 s28, s26, 0xfffc0080
	s_addc_u32 s29, s27, -1
	s_cmp_eq_u32 s84, 12
	s_cselect_b32 s31, s15, s29
	s_cselect_b32 s30, s76, s28
	s_cselect_b32 s29, s13, s83
	s_cselect_b32 s28, s77, s82
	v_lshl_add_u64 v[144:145], s[26:27], 0, v[136:137]
	s_add_i32 m0, s25, 0xc000
	ds_read_b128 v[184:187], v151
	ds_read_b128 v[188:191], v151 offset:1024
	ds_read_b128 v[192:195], v151 offset:2048
	ds_read_b128 v[196:199], v151 offset:3072
	ds_read_b128 v[200:203], v151 offset:4096
	ds_read_b128 v[204:207], v151 offset:5120
	ds_read_b128 v[212:215], v151 offset:6144
	ds_read_b128 v[216:219], v151 offset:7168
	global_load_lds_dwordx4 v[144:145], off
	v_lshl_add_u64 v[144:145], s[26:27], 0, v[138:139]
	s_add_i32 m0, s25, 0xe000
	s_nop 0
	global_load_lds_dwordx4 v[144:145], off
	s_waitcnt vmcnt(8)
	s_waitcnt lgkmcnt(0)
	s_barrier
	s_setprio 1
	s_waitcnt lgkmcnt(0)
	v_mfma_f32_16x16x32_bf16 v[124:127], v[152:155], v[184:187], v[124:127]
	v_mfma_f32_16x16x32_bf16 v[120:123], v[160:163], v[184:187], v[120:123]
	v_mfma_f32_16x16x32_bf16 v[116:119], v[152:155], v[192:195], v[116:119]
	v_mfma_f32_16x16x32_bf16 v[108:111], v[160:163], v[192:195], v[108:111]
	v_mfma_f32_16x16x32_bf16 v[100:103], v[152:155], v[200:203], v[100:103]
	v_mfma_f32_16x16x32_bf16 v[92:95], v[160:163], v[200:203], v[92:95]
	v_mfma_f32_16x16x32_bf16 v[84:87], v[152:155], v[212:215], v[84:87]
	v_mfma_f32_16x16x32_bf16 v[76:79], v[160:163], v[212:215], v[76:79]
	v_mfma_f32_16x16x32_bf16 v[124:127], v[156:159], v[188:191], v[124:127]
	v_mfma_f32_16x16x32_bf16 v[120:123], v[164:167], v[188:191], v[120:123]
	v_mfma_f32_16x16x32_bf16 v[116:119], v[156:159], v[196:199], v[116:119]
	v_mfma_f32_16x16x32_bf16 v[108:111], v[164:167], v[196:199], v[108:111]
	v_mfma_f32_16x16x32_bf16 v[100:103], v[156:159], v[204:207], v[100:103]
	v_mfma_f32_16x16x32_bf16 v[92:95], v[164:167], v[204:207], v[92:95]
	v_mfma_f32_16x16x32_bf16 v[84:87], v[156:159], v[216:219], v[84:87]
	v_mfma_f32_16x16x32_bf16 v[76:79], v[164:167], v[216:219], v[76:79]
	s_setprio 0
	s_setprio 1
	v_mfma_f32_16x16x32_bf16 v[112:115], v[168:171], v[184:187], v[112:115]
	v_mfma_f32_16x16x32_bf16 v[104:107], v[176:179], v[184:187], v[104:107]
	v_mfma_f32_16x16x32_bf16 v[96:99], v[168:171], v[192:195], v[96:99]
	v_mfma_f32_16x16x32_bf16 v[88:91], v[176:179], v[192:195], v[88:91]
	v_mfma_f32_16x16x32_bf16 v[80:83], v[168:171], v[200:203], v[80:83]
	v_mfma_f32_16x16x32_bf16 v[72:75], v[176:179], v[200:203], v[72:75]
	v_mfma_f32_16x16x32_bf16 v[68:71], v[168:171], v[212:215], v[68:71]
	v_mfma_f32_16x16x32_bf16 v[64:67], v[176:179], v[212:215], v[64:67]
	v_mfma_f32_16x16x32_bf16 v[112:115], v[172:175], v[188:191], v[112:115]
	v_mfma_f32_16x16x32_bf16 v[104:107], v[180:183], v[188:191], v[104:107]
	v_mfma_f32_16x16x32_bf16 v[96:99], v[172:175], v[196:199], v[96:99]
	v_mfma_f32_16x16x32_bf16 v[88:91], v[180:183], v[196:199], v[88:91]
	v_mfma_f32_16x16x32_bf16 v[80:83], v[172:175], v[204:207], v[80:83]
	v_mfma_f32_16x16x32_bf16 v[72:75], v[180:183], v[204:207], v[72:75]
	v_mfma_f32_16x16x32_bf16 v[68:71], v[172:175], v[216:219], v[68:71]
	v_mfma_f32_16x16x32_bf16 v[64:67], v[180:183], v[216:219], v[64:67]
	s_setprio 0
	s_barrier
; #define PG8_STAGE(bufoff, gbase, voff) do { _Pragma("unroll") for (int _i = 0; _i < 2; ++_i) \
;         __builtin_amdgcn_global_load_lds((const unsigned*)((const char*)(gbase) + (voff)[_i]), (PG8_LAS unsigned*)(lds + (bufoff) + ldsw + _i * 8192), 16, 0, 0); } while (0)
; #define PG8_LDA(dst, b, h) do { _Pragma("unroll") for (int m = 0; m < 4; ++m) _Pragma("unroll") for (int k = 0; k < 2; ++k) dst[m][k] = *(const PG8_LAS bf16x8*)(lds + PG8_SA(b, h) + aoff + m * 2048 + k * 1024); } while (0)
; #define PG8_LDB(dst, b, h) do { _Pragma("unroll") for (int n = 0; n < 2; ++n) _Pragma("unroll") for (int k = 0; k < 2; ++k) dst[n][k] = *(const PG8_LAS bf16x8*)(lds + PG8_SB(b, h) + boff + n * 2048 + k * 1024); } while (0)
; #define PG8_MMA(ai, bj, At, Bt) do { __builtin_amdgcn_s_setprio(1); _Pragma("unroll") for (int m = 0; m < 4; ++m) _Pragma("unroll") for (int n = 0; n < 2; ++n) _Pragma("unroll") for (int k = 0; k < 2; ++k) \
;         acc[ai][bj][m][n] = __builtin_amdgcn_mfma_f32_16x16x32_bf16(Bt[n][k], At[m][k], acc[ai][bj][m][n], 0, 0, 0); __builtin_amdgcn_s_setprio(0); } while (0)
; #define PG8_WAIT_V(n) asm volatile("s_waitcnt vmcnt(" #n ")" ::: "memory")
; #define PG8_WAIT_L(n) asm volatile("s_waitcnt lgkmcnt(" #n ")" ::: "memory")
; #define PG8_BAR __builtin_amdgcn_s_barrier()
; #define PG8_SCHED __builtin_amdgcn_sched_barrier(0)
; template <class Epi, class Sched, bool ALIGN_EPI = false, bool SP2 = false, bool AROWS128 = false>
; __device__ __forceinline__ void gemm_phase(PG8_LAS unsigned char* lds, const Gemm g, const Sched& S, const Epi& E) {
;     ...
;             PG8_LDA(At, 0, 1); PG8_STAGE(PG8_SB(0, 0), b2, voffB); PG8_STAGE(PG8_SB(0, 1), b2 + hstep, voffB); PG8_STAGE(PG8_SA(0, 0), a2, voffA);
;             PG8_WAIT_V(8); PG8_WAIT_L(0); PG8_BAR; PG8_MMA(1, 0, At, B0); PG8_MMA(1, 1, At, B1); PG8_BAR; PG8_SCHED;
;             PG8_LDB(B0, 1, 0); PG8_LDB(B1, 1, 1); PG8_SCHED; PG8_LDA(At, 1, 0); PG8_STAGE(PG8_SA(0, 1), a2 + hstepA, voffA);
;             PG8_WAIT_V(8); PG8_WAIT_L(0); PG8_BAR; PG8_MMA(0, 0, At, B0); PG8_MMA(0, 1, At, B1); PG8_BAR; PG8_SCHED;
	s_add_i32 s85, s72, s3
	v_lshl_add_u64 v[144:145], s[28:29], 0, v[132:133]
	s_mov_b32 m0, s85
	ds_read_b128 v[184:187], v151 offset:16384
	ds_read_b128 v[188:191], v151 offset:17408
	ds_read_b128 v[192:195], v151 offset:18432
	ds_read_b128 v[196:199], v151 offset:19456
	ds_read_b128 v[200:203], v151 offset:20480
	ds_read_b128 v[204:207], v151 offset:21504
	ds_read_b128 v[212:215], v151 offset:22528
	ds_read_b128 v[216:219], v151 offset:23552
	global_load_lds_dwordx4 v[144:145], off
	s_add_i32 m0, s85, 0x2000
	s_add_u32 s86, s28, 0x40000
	v_lshl_add_u64 v[208:209], s[28:29], 0, v[128:129]
	s_addc_u32 s87, s29, 0
	s_add_i32 s85, s73, s3
	global_load_lds_dwordx4 v[208:209], off
	v_lshl_add_u64 v[220:221], s[86:87], 0, v[132:133]
	s_mov_b32 m0, s85
	v_lshl_add_u64 v[222:223], s[30:31], 0, v[130:131]
	global_load_lds_dwordx4 v[220:221], off
	v_lshl_add_u64 v[220:221], s[86:87], 0, v[128:129]
	s_add_i32 m0, s85, 0x2000
	s_nop 0
	global_load_lds_dwordx4 v[220:221], off
	v_lshl_add_u64 v[220:221], s[30:31], 0, v[134:135]
	s_mov_b32 m0, s25
	s_nop 0
	global_load_lds_dwordx4 v[220:221], off
	s_mov_b32 m0, s50
	s_nop 0
	global_load_lds_dwordx4 v[222:223], off
	s_waitcnt vmcnt(8)
	s_waitcnt lgkmcnt(0)
	s_barrier
	s_setprio 1
	s_waitcnt lgkmcnt(0)
	v_mfma_f32_16x16x32_bf16 v[60:63], v[152:155], v[184:187], v[60:63]
	v_mfma_f32_16x16x32_bf16 v[56:59], v[160:163], v[184:187], v[56:59]
	v_mfma_f32_16x16x32_bf16 v[52:55], v[152:155], v[192:195], v[52:55]
	v_mfma_f32_16x16x32_bf16 v[44:47], v[160:163], v[192:195], v[44:47]
	v_mfma_f32_16x16x32_bf16 v[36:39], v[152:155], v[200:203], v[36:39]
	v_mfma_f32_16x16x32_bf16 v[28:31], v[160:163], v[200:203], v[28:31]
	v_mfma_f32_16x16x32_bf16 v[20:23], v[152:155], v[212:215], v[20:23]
	v_mfma_f32_16x16x32_bf16 v[12:15], v[160:163], v[212:215], v[12:15]
	v_mfma_f32_16x16x32_bf16 v[60:63], v[156:159], v[188:191], v[60:63]
	v_mfma_f32_16x16x32_bf16 v[56:59], v[164:167], v[188:191], v[56:59]
	v_mfma_f32_16x16x32_bf16 v[52:55], v[156:159], v[196:199], v[52:55]
	v_mfma_f32_16x16x32_bf16 v[44:47], v[164:167], v[196:199], v[44:47]
	v_mfma_f32_16x16x32_bf16 v[36:39], v[156:159], v[204:207], v[36:39]
	v_mfma_f32_16x16x32_bf16 v[28:31], v[164:167], v[204:207], v[28:31]
	v_mfma_f32_16x16x32_bf16 v[20:23], v[156:159], v[216:219], v[20:23]
	v_mfma_f32_16x16x32_bf16 v[12:15], v[164:167], v[216:219], v[12:15]
	s_setprio 0
	s_setprio 1
	v_mfma_f32_16x16x32_bf16 v[48:51], v[168:171], v[184:187], v[48:51]
	v_mfma_f32_16x16x32_bf16 v[40:43], v[176:179], v[184:187], v[40:43]
	v_mfma_f32_16x16x32_bf16 v[32:35], v[168:171], v[192:195], v[32:35]
	v_mfma_f32_16x16x32_bf16 v[24:27], v[176:179], v[192:195], v[24:27]
	v_mfma_f32_16x16x32_bf16 v[16:19], v[168:171], v[200:203], v[16:19]
	v_mfma_f32_16x16x32_bf16 v[8:11], v[176:179], v[200:203], v[8:11]
	v_mfma_f32_16x16x32_bf16 v[4:7], v[168:171], v[212:215], v[4:7]
	v_mfma_f32_16x16x32_bf16 v[0:3], v[176:179], v[212:215], v[0:3]
	v_mfma_f32_16x16x32_bf16 v[48:51], v[172:175], v[188:191], v[48:51]
	v_mfma_f32_16x16x32_bf16 v[40:43], v[180:183], v[188:191], v[40:43]
	v_mfma_f32_16x16x32_bf16 v[32:35], v[172:175], v[196:199], v[32:35]
	v_mfma_f32_16x16x32_bf16 v[24:27], v[180:183], v[196:199], v[24:27]
	v_mfma_f32_16x16x32_bf16 v[16:19], v[172:175], v[204:207], v[16:19]
	v_mfma_f32_16x16x32_bf16 v[8:11], v[180:183], v[204:207], v[8:11]
	v_mfma_f32_16x16x32_bf16 v[4:7], v[172:175], v[216:219], v[4:7]
	v_mfma_f32_16x16x32_bf16 v[0:3], v[180:183], v[216:219], v[0:3]
	s_setprio 0
	s_barrier
	s_add_i32 s85, 0, 0x18000
	s_add_i32 s86, 0, 0x1c000
	v_add_u32_e32 v164, s85, v147
	v_add_u32_e32 v180, s86, v147
	ds_read_b128 v[152:155], v164
	ds_read_b128 v[156:159], v164 offset:1024
	ds_read_b128 v[160:163], v164 offset:2048
	ds_read_b128 v[164:167], v164 offset:3072
	ds_read_b128 v[168:171], v180
	ds_read_b128 v[172:175], v180 offset:1024
	ds_read_b128 v[176:179], v180 offset:2048
	ds_read_b128 v[180:183], v180 offset:3072
	s_add_u32 s30, s30, 0x40000
	s_addc_u32 s31, s31, 0
	s_mov_b32 m0, s51
	v_lshl_add_u64 v[224:225], s[30:31], 0, v[134:135]
	ds_read_b128 v[184:187], v151 offset:32768
	ds_read_b128 v[188:191], v151 offset:33792
	ds_read_b128 v[192:195], v151 offset:34816
	ds_read_b128 v[196:199], v151 offset:35840
	ds_read_b128 v[200:203], v151 offset:36864
	ds_read_b128 v[204:207], v151 offset:37888
	ds_read_b128 v[212:215], v151 offset:38912
	ds_read_b128 v[216:219], v151 offset:39936
	global_load_lds_dwordx4 v[224:225], off
	v_lshl_add_u64 v[224:225], s[30:31], 0, v[130:131]
	s_mov_b32 m0, s52
	s_nop 0
	global_load_lds_dwordx4 v[224:225], off
	s_waitcnt vmcnt(8)
	s_waitcnt lgkmcnt(0)
	s_barrier
; #define PG8_STAGE(bufoff, gbase, voff) do { _Pragma("unroll") for (int _i = 0; _i < 2; ++_i) \
;         __builtin_amdgcn_global_load_lds((const unsigned*)((const char*)(gbase) + (voff)[_i]), (PG8_LAS unsigned*)(lds + (bufoff) + ldsw + _i * 8192), 16, 0, 0); } while (0)
; #define PG8_LDA(dst, b, h) do { _Pragma("unroll") for (int m = 0; m < 4; ++m) _Pragma("unroll") for (int k = 0; k < 2; ++k) dst[m][k] = *(const PG8_LAS bf16x8*)(lds + PG8_SA(b, h) + aoff + m * 2048 + k * 1024); } while (0)
; #define PG8_MMA(ai, bj, At, Bt) do { __builtin_amdgcn_s_setprio(1); _Pragma("unroll") for (int m = 0; m < 4; ++m) _Pragma("unroll") for (int n = 0; n < 2; ++n) _Pragma("unroll") for (int k = 0; k < 2; ++k) \
;         acc[ai][bj][m][n] = __builtin_amdgcn_mfma_f32_16x16x32_bf16(Bt[n][k], At[m][k], acc[ai][bj][m][n], 0, 0, 0); __builtin_amdgcn_s_setprio(0); } while (0)
; #define PG8_WAIT_V(n) asm volatile("s_waitcnt vmcnt(" #n ")" ::: "memory")
; #define PG8_WAIT_L(n) asm volatile("s_waitcnt lgkmcnt(" #n ")" ::: "memory")
; #define PG8_BAR __builtin_amdgcn_s_barrier()
; #define PG8_SCHED __builtin_amdgcn_sched_barrier(0)
; template <class Epi, class Sched, bool ALIGN_EPI = false, bool SP2 = false, bool AROWS128 = false>
; __device__ __forceinline__ void gemm_phase(PG8_LAS unsigned char* lds, const Gemm g, const Sched& S, const Epi& E) {
;     ...
;         for (int t = 0; t < nt; t += 2) {
;     ...
;             PG8_WAIT_V(8); PG8_WAIT_L(0); PG8_BAR; PG8_MMA(0, 0, At, B0); PG8_MMA(0, 1, At, B1); PG8_BAR; PG8_SCHED;
;             PG8_LDA(At, 1, 1); PG8_STAGE(PG8_SB(1, 0), b3, voffB); PG8_STAGE(PG8_SB(1, 1), b3 + hstep, voffB); PG8_STAGE(PG8_SA(1, 0), a3, voffA);
;             PG8_WAIT_V(8); PG8_WAIT_L(0); PG8_BAR; PG8_MMA(1, 0, At, B0); PG8_MMA(1, 1, At, B1); PG8_BAR; PG8_SCHED;
	s_setprio 1
	s_waitcnt lgkmcnt(0)
	v_mfma_f32_16x16x32_bf16 v[124:127], v[152:155], v[184:187], v[124:127]
	v_mfma_f32_16x16x32_bf16 v[120:123], v[160:163], v[184:187], v[120:123]
	v_mfma_f32_16x16x32_bf16 v[116:119], v[152:155], v[192:195], v[116:119]
	v_mfma_f32_16x16x32_bf16 v[108:111], v[160:163], v[192:195], v[108:111]
	v_mfma_f32_16x16x32_bf16 v[100:103], v[152:155], v[200:203], v[100:103]
	v_mfma_f32_16x16x32_bf16 v[92:95], v[160:163], v[200:203], v[92:95]
	v_mfma_f32_16x16x32_bf16 v[84:87], v[152:155], v[212:215], v[84:87]
	v_mfma_f32_16x16x32_bf16 v[76:79], v[160:163], v[212:215], v[76:79]
	v_mfma_f32_16x16x32_bf16 v[124:127], v[156:159], v[188:191], v[124:127]
	v_mfma_f32_16x16x32_bf16 v[120:123], v[164:167], v[188:191], v[120:123]
	v_mfma_f32_16x16x32_bf16 v[116:119], v[156:159], v[196:199], v[116:119]
	v_mfma_f32_16x16x32_bf16 v[108:111], v[164:167], v[196:199], v[108:111]
	v_mfma_f32_16x16x32_bf16 v[100:103], v[156:159], v[204:207], v[100:103]
	v_mfma_f32_16x16x32_bf16 v[92:95], v[164:167], v[204:207], v[92:95]
	v_mfma_f32_16x16x32_bf16 v[84:87], v[156:159], v[216:219], v[84:87]
	v_mfma_f32_16x16x32_bf16 v[76:79], v[164:167], v[216:219], v[76:79]
	s_setprio 0
	s_setprio 1
	v_mfma_f32_16x16x32_bf16 v[112:115], v[168:171], v[184:187], v[112:115]
	v_mfma_f32_16x16x32_bf16 v[104:107], v[176:179], v[184:187], v[104:107]
	v_mfma_f32_16x16x32_bf16 v[96:99], v[168:171], v[192:195], v[96:99]
	v_mfma_f32_16x16x32_bf16 v[88:91], v[176:179], v[192:195], v[88:91]
	v_mfma_f32_16x16x32_bf16 v[80:83], v[168:171], v[200:203], v[80:83]
	v_mfma_f32_16x16x32_bf16 v[72:75], v[176:179], v[200:203], v[72:75]
	v_mfma_f32_16x16x32_bf16 v[68:71], v[168:171], v[212:215], v[68:71]
	v_mfma_f32_16x16x32_bf16 v[64:67], v[176:179], v[212:215], v[64:67]
	v_mfma_f32_16x16x32_bf16 v[112:115], v[172:175], v[188:191], v[112:115]
	v_mfma_f32_16x16x32_bf16 v[104:107], v[180:183], v[188:191], v[104:107]
	v_mfma_f32_16x16x32_bf16 v[96:99], v[172:175], v[196:199], v[96:99]
	v_mfma_f32_16x16x32_bf16 v[88:91], v[180:183], v[196:199], v[88:91]
	v_mfma_f32_16x16x32_bf16 v[80:83], v[172:175], v[204:207], v[80:83]
	v_mfma_f32_16x16x32_bf16 v[72:75], v[180:183], v[204:207], v[72:75]
	v_mfma_f32_16x16x32_bf16 v[68:71], v[172:175], v[216:219], v[68:71]
	v_mfma_f32_16x16x32_bf16 v[64:67], v[180:183], v[216:219], v[64:67]
	s_setprio 0
	s_barrier
	s_add_i32 s30, s85, s3
	v_lshl_add_u64 v[144:145], v[144:145], 0, s[6:7]
	s_mov_b32 m0, s30
	ds_read_b128 v[184:187], v151 offset:49152
	ds_read_b128 v[188:191], v151 offset:50176
	ds_read_b128 v[192:195], v151 offset:51200
	ds_read_b128 v[196:199], v151 offset:52224
	ds_read_b128 v[200:203], v151 offset:53248
	ds_read_b128 v[204:207], v151 offset:54272
	ds_read_b128 v[212:215], v151 offset:55296
	ds_read_b128 v[216:219], v151 offset:56320
	global_load_lds_dwordx4 v[144:145], off
	s_add_i32 m0, s30, 0x2000
	s_add_u32 s28, s28, 0x40080
	v_lshl_add_u64 v[144:145], v[208:209], 0, s[6:7]
	s_addc_u32 s29, s29, 0
	s_add_i32 s30, s86, s3
	global_load_lds_dwordx4 v[144:145], off
	v_lshl_add_u64 v[144:145], s[28:29], 0, v[132:133]
	s_mov_b32 m0, s30
	s_nop 0
	global_load_lds_dwordx4 v[144:145], off
	v_lshl_add_u64 v[144:145], s[28:29], 0, v[128:129]
	s_add_i32 m0, s30, 0x2000
	s_nop 0
	global_load_lds_dwordx4 v[144:145], off
	v_lshl_add_u64 v[144:145], v[220:221], 0, s[6:7]
	s_mov_b32 m0, s58
	s_nop 0
	global_load_lds_dwordx4 v[144:145], off
	v_lshl_add_u64 v[144:145], v[222:223], 0, s[6:7]
	s_mov_b32 m0, s59
	s_nop 0
	global_load_lds_dwordx4 v[144:145], off
	s_waitcnt vmcnt(8)
	s_waitcnt lgkmcnt(0)
	s_barrier
	s_setprio 1
	s_waitcnt lgkmcnt(0)
	v_mfma_f32_16x16x32_bf16 v[60:63], v[152:155], v[184:187], v[60:63]
	v_mfma_f32_16x16x32_bf16 v[56:59], v[160:163], v[184:187], v[56:59]
	v_mfma_f32_16x16x32_bf16 v[52:55], v[152:155], v[192:195], v[52:55]
	v_mfma_f32_16x16x32_bf16 v[44:47], v[160:163], v[192:195], v[44:47]
	v_mfma_f32_16x16x32_bf16 v[36:39], v[152:155], v[200:203], v[36:39]
	v_mfma_f32_16x16x32_bf16 v[28:31], v[160:163], v[200:203], v[28:31]
	v_mfma_f32_16x16x32_bf16 v[20:23], v[152:155], v[212:215], v[20:23]
	v_mfma_f32_16x16x32_bf16 v[12:15], v[160:163], v[212:215], v[12:15]
	v_mfma_f32_16x16x32_bf16 v[60:63], v[156:159], v[188:191], v[60:63]
	v_mfma_f32_16x16x32_bf16 v[56:59], v[164:167], v[188:191], v[56:59]
	v_mfma_f32_16x16x32_bf16 v[52:55], v[156:159], v[196:199], v[52:55]
	v_mfma_f32_16x16x32_bf16 v[44:47], v[164:167], v[196:199], v[44:47]
	v_mfma_f32_16x16x32_bf16 v[36:39], v[156:159], v[204:207], v[36:39]
	v_mfma_f32_16x16x32_bf16 v[28:31], v[164:167], v[204:207], v[28:31]
	v_mfma_f32_16x16x32_bf16 v[20:23], v[156:159], v[216:219], v[20:23]
	v_mfma_f32_16x16x32_bf16 v[12:15], v[164:167], v[216:219], v[12:15]
	s_setprio 0
	s_setprio 1
	v_mfma_f32_16x16x32_bf16 v[48:51], v[168:171], v[184:187], v[48:51]
	v_mfma_f32_16x16x32_bf16 v[40:43], v[176:179], v[184:187], v[40:43]
	v_mfma_f32_16x16x32_bf16 v[32:35], v[168:171], v[192:195], v[32:35]
	v_mfma_f32_16x16x32_bf16 v[24:27], v[176:179], v[192:195], v[24:27]
	v_mfma_f32_16x16x32_bf16 v[16:19], v[168:171], v[200:203], v[16:19]
	v_mfma_f32_16x16x32_bf16 v[8:11], v[176:179], v[200:203], v[8:11]
	v_mfma_f32_16x16x32_bf16 v[4:7], v[168:171], v[212:215], v[4:7]
	v_mfma_f32_16x16x32_bf16 v[0:3], v[176:179], v[212:215], v[0:3]
	v_mfma_f32_16x16x32_bf16 v[48:51], v[172:175], v[188:191], v[48:51]
	v_mfma_f32_16x16x32_bf16 v[40:43], v[180:183], v[188:191], v[40:43]
	v_mfma_f32_16x16x32_bf16 v[32:35], v[172:175], v[196:199], v[32:35]
	v_mfma_f32_16x16x32_bf16 v[24:27], v[180:183], v[196:199], v[24:27]
	v_mfma_f32_16x16x32_bf16 v[16:19], v[172:175], v[204:207], v[16:19]
	v_mfma_f32_16x16x32_bf16 v[8:11], v[180:183], v[204:207], v[8:11]
	v_mfma_f32_16x16x32_bf16 v[4:7], v[172:175], v[216:219], v[4:7]
	v_mfma_f32_16x16x32_bf16 v[0:3], v[180:183], v[216:219], v[0:3]
	s_setprio 0
	s_barrier
	s_add_i32 s84, s84, 2
	s_add_u32 s26, s26, 0x100
	s_addc_u32 s27, s27, 0
	s_add_u32 s82, s82, 0x100
	s_addc_u32 s83, s83, 0
	s_cmp_gt_u32 s84, 13
	s_cbranch_scc0 .LBB0_489
	s_nop 0
	s_and_b64 vcc, exec, s[8:9]
	s_cbranch_vccz .LBB0_492
	s_barrier

; #define PG8_STAGE(bufoff, gbase, voff) do { _Pragma("unroll") for (int _i = 0; _i < 2; ++_i) \
;         __builtin_amdgcn_global_load_lds((const unsigned*)((const char*)(gbase) + (voff)[_i]), (PG8_LAS unsigned*)(lds + (bufoff) + ldsw + _i * 8192), 16, 0, 0); } while (0)
; #define PG8_LDA(dst, b, h) do { _Pragma("unroll") for (int m = 0; m < 4; ++m) _Pragma("unroll") for (int k = 0; k < 2; ++k) dst[m][k] = *(const PG8_LAS bf16x8*)(lds + PG8_SA(b, h) + aoff + m * 2048 + k * 1024); } while (0)
; #define PG8_LDB(dst, b, h) do { _Pragma("unroll") for (int n = 0; n < 2; ++n) _Pragma("unroll") for (int k = 0; k < 2; ++k) dst[n][k] = *(const PG8_LAS bf16x8*)(lds + PG8_SB(b, h) + boff + n * 2048 + k * 1024); } while (0)
; #define PG8_WAIT_V(n) asm volatile("s_waitcnt vmcnt(" #n ")" ::: "memory")
; #define PG8_WAIT_L(n) asm volatile("s_waitcnt lgkmcnt(" #n ")" ::: "memory")
; #define PG8_BAR __builtin_amdgcn_s_barrier()
; #define PG8_SCHED __builtin_amdgcn_sched_barrier(0)
; template <class Epi, class Sched, bool ALIGN_EPI = false, bool SP2 = false, bool AROWS128 = false>
; __device__ __forceinline__ void gemm_phase(PG8_LAS unsigned char* lds, const Gemm g, const Sched& S, const Epi& E) {
;     ...
;         const char* nA = has_next ? (const char*)g.A + (size_t)nxt.pm * tstep : cA; const char* nB = has_next ? (const char*)g.Bt + (size_t)nxt.pn * tstep : cB;
;         for (int t = 0; t < nt; t += 2) {
;             const bool last = (t == nt - 2);
;             const char* a1 = cA + (size_t)(t + 1) * kstep;
;             const char* a2 = last ? nA : cA + (size_t)(t + 2) * kstep; const char* b2 = last ? nB : cB + (size_t)(t + 2) * kstep;
;             const char* a3 = a2 + kstep; const char* b3 = b2 + kstep;
;             if (last && has_next) S.a_ready(nxt);
;             if constexpr (SP2) {
;             PG8_LDB(B0, 0, 0); PG8_LDB(B1, 0, 1); PG8_SCHED; PG8_LDA(At, 0, 0); PG8_STAGE(PG8_SA(1, 1), a1 + hstepA, voffA);
;             PG8_WAIT_V(8); PG8_WAIT_L(0); PG8_BAR; PG8_MMA(0, 0, At, B0); PG8_MMA(0, 1, At, B1); PG8_BAR; PG8_SCHED;
;     ...
; #pragma unroll
;         for (int a = 0; a < 2; ++a)
; #pragma unroll
;             for (int b = 0; b < 2; ++b)
; #pragma unroll
;                 for (int m = 0; m < 4; ++m)
; #pragma unroll
;                     for (int n = 0; n < 2; ++n) acc[a][b][m][n] = (f32x4){0.f, 0.f, 0.f, 0.f};
.LBB0_625:
	v_mov_b32_e32 v236, s16
	v_lshlrev_b32_e32 v236, 9, v236
	v_mov_b32_e32 v237, 0
	v_lshl_add_u64 v[232:233], v[230:231], 0, v[236:237]
	s_lshr_b32 m0, s84, 1
	s_add_i32 m0, m0, 0x21000
	s_mov_b32 exec_hi, 0
	global_load_lds_dwordx4 v[232:233], off
	s_mov_b32 exec_hi, -1
	s_ashr_i32 s55, s54, 31
	s_lshl_b64 s[56:57], s[54:55], 19
	s_add_u32 s56, s46, s56
	s_addc_u32 s57, s47, s57
	s_and_b64 s[58:59], s[14:15], exec
	s_cselect_b32 s17, s57, s19
	s_cselect_b32 s33, s56, s18
	s_ashr_i32 s53, s52, 31
	s_lshl_b64 s[58:59], s[52:53], 19
	s_add_u32 s58, s78, s58
	s_addc_u32 s59, s79, s59
	s_and_b64 s[72:73], s[14:15], exec
	s_cselect_b32 s53, s59, s21
	s_cselect_b32 s55, s58, s20
	s_add_u32 s18, s18, 0x20080
	s_addc_u32 s19, s19, 0
	s_add_u32 s65, s20, 0x100
	v_mov_b32_e32 v0, 0
	s_addc_u32 s72, s21, 0
	s_mov_b32 s73, -2
	v_mov_b64_e32 v[0:1], 0
	v_mov_b64_e32 v[2:3], 0
	v_mov_b64_e32 v[4:5], 0
	v_mov_b64_e32 v[6:7], 0
	v_mov_b64_e32 v[8:9], 0
	v_mov_b64_e32 v[10:11], 0
	v_mov_b64_e32 v[12:13], 0
	v_mov_b64_e32 v[14:15], 0
	v_mov_b64_e32 v[16:17], 0
	v_mov_b64_e32 v[18:19], 0
	v_mov_b64_e32 v[20:21], 0
	v_mov_b64_e32 v[22:23], 0
	v_mov_b64_e32 v[24:25], 0
	v_mov_b64_e32 v[26:27], 0
	v_mov_b64_e32 v[28:29], 0
	v_mov_b64_e32 v[30:31], 0
	v_mov_b64_e32 v[32:33], 0
	v_mov_b64_e32 v[34:35], 0
	v_mov_b64_e32 v[36:37], 0
	v_mov_b64_e32 v[38:39], 0
	v_mov_b64_e32 v[40:41], 0
	v_mov_b64_e32 v[42:43], 0
	v_mov_b64_e32 v[44:45], 0
	v_mov_b64_e32 v[46:47], 0
	v_mov_b64_e32 v[48:49], 0
	v_mov_b64_e32 v[50:51], 0
	v_mov_b64_e32 v[52:53], 0
	v_mov_b64_e32 v[54:55], 0
	v_mov_b64_e32 v[56:57], 0
	v_mov_b64_e32 v[58:59], 0
	v_mov_b64_e32 v[60:61], 0
	v_mov_b64_e32 v[62:63], 0
	v_mov_b64_e32 v[64:65], 0
	v_mov_b64_e32 v[66:67], 0
	v_mov_b64_e32 v[68:69], 0
	v_mov_b64_e32 v[70:71], 0
	v_mov_b64_e32 v[104:105], 0
	v_mov_b64_e32 v[106:107], 0
	v_mov_b64_e32 v[108:109], 0
	v_mov_b64_e32 v[110:111], 0
	v_mov_b64_e32 v[112:113], 0
	v_mov_b64_e32 v[114:115], 0
	v_mov_b64_e32 v[116:117], 0
	v_mov_b64_e32 v[118:119], 0
	v_mov_b64_e32 v[120:121], 0
	v_mov_b64_e32 v[122:123], 0
	v_mov_b64_e32 v[124:125], 0
	v_mov_b64_e32 v[126:127], 0
	v_mov_b64_e32 v[128:129], 0
	v_mov_b64_e32 v[130:131], 0
	v_mov_b64_e32 v[132:133], 0
	v_mov_b64_e32 v[134:135], 0
	v_mov_b64_e32 v[136:137], 0
	v_mov_b64_e32 v[138:139], 0
	v_mov_b64_e32 v[140:141], 0
	v_mov_b64_e32 v[142:143], 0
	v_mov_b64_e32 v[144:145], 0
	v_mov_b64_e32 v[146:147], 0
	v_mov_b64_e32 v[148:149], 0
	v_mov_b64_e32 v[150:151], 0
	v_mov_b64_e32 v[152:153], 0
	v_mov_b64_e32 v[154:155], 0
	v_mov_b64_e32 v[156:157], 0
	v_mov_b64_e32 v[158:159], 0
	s_nop 0
.LBB0_626:
	ds_read_b128 v[72:75], v207
	ds_read_b128 v[76:79], v207 offset:1024
	ds_read_b128 v[80:83], v207 offset:2048
	ds_read_b128 v[84:87], v207 offset:3072
	ds_read_b128 v[88:91], v208
	ds_read_b128 v[92:95], v208 offset:1024
	ds_read_b128 v[96:99], v208 offset:2048
	ds_read_b128 v[100:103], v208 offset:3072
	s_add_u32 s20, s18, 0xfffe0080
	s_addc_u32 s21, s19, -1
	s_cmp_eq_u32 s73, 12
	s_cselect_b32 s81, s17, s21
	s_cselect_b32 s80, s33, s20
	s_cselect_b32 s21, s53, s72
	s_cselect_b32 s20, s55, s65
	v_lshl_add_u64 v[220:221], s[18:19], 0, v[168:169]
	s_add_i32 m0, s84, 0xc000
	ds_read_b128 v[176:179], v209
	ds_read_b128 v[180:183], v209 offset:1024
	ds_read_b128 v[184:187], v209 offset:2048
	ds_read_b128 v[188:191], v209 offset:3072
	ds_read_b128 v[192:195], v209 offset:4096
	ds_read_b128 v[196:199], v209 offset:5120
	ds_read_b128 v[212:215], v209 offset:6144
	ds_read_b128 v[216:219], v209 offset:7168
	global_load_lds_dwordx4 v[220:221], off
	v_lshl_add_u64 v[220:221], s[18:19], 0, v[170:171]
	s_add_i32 m0, s84, 0xe000
	s_nop 0
	global_load_lds_dwordx4 v[220:221], off
	s_waitcnt vmcnt(8)
	s_waitcnt lgkmcnt(0)
	s_barrier
	s_setprio 1
	s_waitcnt lgkmcnt(0)
	v_mfma_f32_16x16x32_bf16 v[36:39], v[72:75], v[176:179], v[36:39]
	v_mfma_f32_16x16x32_bf16 v[28:31], v[80:83], v[176:179], v[28:31]
	v_mfma_f32_16x16x32_bf16 v[140:143], v[72:75], v[184:187], v[140:143]
	v_mfma_f32_16x16x32_bf16 v[136:139], v[80:83], v[184:187], v[136:139]
	v_mfma_f32_16x16x32_bf16 v[124:127], v[72:75], v[192:195], v[124:127]
	v_mfma_f32_16x16x32_bf16 v[120:123], v[80:83], v[192:195], v[120:123]
	v_mfma_f32_16x16x32_bf16 v[108:111], v[72:75], v[212:215], v[108:111]
	v_mfma_f32_16x16x32_bf16 v[104:107], v[80:83], v[212:215], v[104:107]
	v_mfma_f32_16x16x32_bf16 v[36:39], v[76:79], v[180:183], v[36:39]
	v_mfma_f32_16x16x32_bf16 v[28:31], v[84:87], v[180:183], v[28:31]
	v_mfma_f32_16x16x32_bf16 v[140:143], v[76:79], v[188:191], v[140:143]
	v_mfma_f32_16x16x32_bf16 v[136:139], v[84:87], v[188:191], v[136:139]
	v_mfma_f32_16x16x32_bf16 v[124:127], v[76:79], v[196:199], v[124:127]
	v_mfma_f32_16x16x32_bf16 v[120:123], v[84:87], v[196:199], v[120:123]
	v_mfma_f32_16x16x32_bf16 v[108:111], v[76:79], v[216:219], v[108:111]
	v_mfma_f32_16x16x32_bf16 v[104:107], v[84:87], v[216:219], v[104:107]
	s_setprio 0
	s_setprio 1
	v_mfma_f32_16x16x32_bf16 v[156:159], v[88:91], v[176:179], v[156:159]
	v_mfma_f32_16x16x32_bf16 v[152:155], v[96:99], v[176:179], v[152:155]
	v_mfma_f32_16x16x32_bf16 v[148:151], v[88:91], v[184:187], v[148:151]
	v_mfma_f32_16x16x32_bf16 v[144:147], v[96:99], v[184:187], v[144:147]
	v_mfma_f32_16x16x32_bf16 v[132:135], v[88:91], v[192:195], v[132:135]
	v_mfma_f32_16x16x32_bf16 v[128:131], v[96:99], v[192:195], v[128:131]
	v_mfma_f32_16x16x32_bf16 v[116:119], v[88:91], v[212:215], v[116:119]
	v_mfma_f32_16x16x32_bf16 v[112:115], v[96:99], v[212:215], v[112:115]
	v_mfma_f32_16x16x32_bf16 v[156:159], v[92:95], v[180:183], v[156:159]
	v_mfma_f32_16x16x32_bf16 v[152:155], v[100:103], v[180:183], v[152:155]
	v_mfma_f32_16x16x32_bf16 v[148:151], v[92:95], v[188:191], v[148:151]
	v_mfma_f32_16x16x32_bf16 v[144:147], v[100:103], v[188:191], v[144:147]
	v_mfma_f32_16x16x32_bf16 v[132:135], v[92:95], v[196:199], v[132:135]
	v_mfma_f32_16x16x32_bf16 v[128:131], v[100:103], v[196:199], v[128:131]
	v_mfma_f32_16x16x32_bf16 v[116:119], v[92:95], v[216:219], v[116:119]
	v_mfma_f32_16x16x32_bf16 v[112:115], v[100:103], v[216:219], v[112:115]
	s_setprio 0
	s_barrier
; #define PG8_STAGE(bufoff, gbase, voff) do { _Pragma("unroll") for (int _i = 0; _i < 2; ++_i) \
;         __builtin_amdgcn_global_load_lds((const unsigned*)((const char*)(gbase) + (voff)[_i]), (PG8_LAS unsigned*)(lds + (bufoff) + ldsw + _i * 8192), 16, 0, 0); } while (0)
; #define PG8_LDA(dst, b, h) do { _Pragma("unroll") for (int m = 0; m < 4; ++m) _Pragma("unroll") for (int k = 0; k < 2; ++k) dst[m][k] = *(const PG8_LAS bf16x8*)(lds + PG8_SA(b, h) + aoff + m * 2048 + k * 1024); } while (0)
; #define PG8_LDB(dst, b, h) do { _Pragma("unroll") for (int n = 0; n < 2; ++n) _Pragma("unroll") for (int k = 0; k < 2; ++k) dst[n][k] = *(const PG8_LAS bf16x8*)(lds + PG8_SB(b, h) + boff + n * 2048 + k * 1024); } while (0)
; #define PG8_MMA(ai, bj, At, Bt) do { __builtin_amdgcn_s_setprio(1); _Pragma("unroll") for (int m = 0; m < 4; ++m) _Pragma("unroll") for (int n = 0; n < 2; ++n) _Pragma("unroll") for (int k = 0; k < 2; ++k) \
;         acc[ai][bj][m][n] = __builtin_amdgcn_mfma_f32_16x16x32_bf16(Bt[n][k], At[m][k], acc[ai][bj][m][n], 0, 0, 0); __builtin_amdgcn_s_setprio(0); } while (0)
; #define PG8_WAIT_V(n) asm volatile("s_waitcnt vmcnt(" #n ")" ::: "memory")
; #define PG8_WAIT_L(n) asm volatile("s_waitcnt lgkmcnt(" #n ")" ::: "memory")
; #define PG8_BAR __builtin_amdgcn_s_barrier()
; #define PG8_SCHED __builtin_amdgcn_sched_barrier(0)
; template <class Epi, class Sched, bool ALIGN_EPI = false, bool SP2 = false, bool AROWS128 = false>
; __device__ __forceinline__ void gemm_phase(PG8_LAS unsigned char* lds, const Gemm g, const Sched& S, const Epi& E) {
;     ...
;             PG8_LDA(At, 0, 1); PG8_STAGE(PG8_SB(0, 0), b2, voffB); PG8_STAGE(PG8_SB(0, 1), b2 + hstep, voffB); PG8_STAGE(PG8_SA(0, 0), a2, voffA);
;             PG8_WAIT_V(8); PG8_WAIT_L(0); PG8_BAR; PG8_MMA(1, 0, At, B0); PG8_MMA(1, 1, At, B1); PG8_BAR; PG8_SCHED;
;             PG8_LDB(B0, 1, 0); PG8_LDB(B1, 1, 1); PG8_SCHED; PG8_LDA(At, 1, 0); PG8_STAGE(PG8_SA(0, 1), a2 + hstepA, voffA);
;             PG8_WAIT_V(8); PG8_WAIT_L(0); PG8_BAR; PG8_MMA(0, 0, At, B0); PG8_MMA(0, 1, At, B1); PG8_BAR; PG8_SCHED;
	s_add_i32 s76, s3, s35
	v_lshl_add_u64 v[220:221], s[20:21], 0, v[162:163]
	s_mov_b32 m0, s76
	ds_read_b128 v[176:179], v209 offset:16384
	ds_read_b128 v[180:183], v209 offset:17408
	ds_read_b128 v[184:187], v209 offset:18432
	ds_read_b128 v[188:191], v209 offset:19456
	ds_read_b128 v[192:195], v209 offset:20480
	ds_read_b128 v[196:199], v209 offset:21504
	ds_read_b128 v[212:215], v209 offset:22528
	ds_read_b128 v[216:219], v209 offset:23552
	global_load_lds_dwordx4 v[220:221], off
	s_add_i32 m0, s76, 0x2000
	s_add_u32 s76, s20, 0x40000
	v_lshl_add_u64 v[222:223], s[20:21], 0, v[166:167]
	s_addc_u32 s77, s21, 0
	s_add_i32 s82, s95, s35
	global_load_lds_dwordx4 v[222:223], off
	v_lshl_add_u64 v[224:225], s[76:77], 0, v[162:163]
	s_mov_b32 m0, s82
	v_lshl_add_u64 v[226:227], s[80:81], 0, v[164:165]
	global_load_lds_dwordx4 v[224:225], off
	v_lshl_add_u64 v[224:225], s[76:77], 0, v[166:167]
	s_add_i32 m0, s82, 0x2000
	s_nop 0
	global_load_lds_dwordx4 v[224:225], off
	v_lshl_add_u64 v[224:225], s[80:81], 0, v[160:161]
	s_mov_b32 m0, s84
	s_nop 0
	global_load_lds_dwordx4 v[224:225], off
	s_mov_b32 m0, s85
	s_nop 0
	global_load_lds_dwordx4 v[226:227], off
	s_waitcnt vmcnt(8)
	s_waitcnt lgkmcnt(0)
	s_barrier
	s_setprio 1
	s_waitcnt lgkmcnt(0)
	v_mfma_f32_16x16x32_bf16 v[60:63], v[72:75], v[176:179], v[60:63]
	v_mfma_f32_16x16x32_bf16 v[56:59], v[80:83], v[176:179], v[56:59]
	v_mfma_f32_16x16x32_bf16 v[44:47], v[72:75], v[184:187], v[44:47]
	v_mfma_f32_16x16x32_bf16 v[40:43], v[80:83], v[184:187], v[40:43]
	v_mfma_f32_16x16x32_bf16 v[20:23], v[72:75], v[192:195], v[20:23]
	v_mfma_f32_16x16x32_bf16 v[16:19], v[80:83], v[192:195], v[16:19]
	v_mfma_f32_16x16x32_bf16 v[12:15], v[72:75], v[212:215], v[12:15]
	v_mfma_f32_16x16x32_bf16 v[8:11], v[80:83], v[212:215], v[8:11]
	v_mfma_f32_16x16x32_bf16 v[60:63], v[76:79], v[180:183], v[60:63]
	v_mfma_f32_16x16x32_bf16 v[56:59], v[84:87], v[180:183], v[56:59]
	v_mfma_f32_16x16x32_bf16 v[44:47], v[76:79], v[188:191], v[44:47]
	v_mfma_f32_16x16x32_bf16 v[40:43], v[84:87], v[188:191], v[40:43]
	v_mfma_f32_16x16x32_bf16 v[20:23], v[76:79], v[196:199], v[20:23]
	v_mfma_f32_16x16x32_bf16 v[16:19], v[84:87], v[196:199], v[16:19]
	v_mfma_f32_16x16x32_bf16 v[12:15], v[76:79], v[216:219], v[12:15]
	v_mfma_f32_16x16x32_bf16 v[8:11], v[84:87], v[216:219], v[8:11]
	s_setprio 0
	s_setprio 1
	v_mfma_f32_16x16x32_bf16 v[68:71], v[88:91], v[176:179], v[68:71]
	v_mfma_f32_16x16x32_bf16 v[64:67], v[96:99], v[176:179], v[64:67]
	v_mfma_f32_16x16x32_bf16 v[52:55], v[88:91], v[184:187], v[52:55]
	v_mfma_f32_16x16x32_bf16 v[48:51], v[96:99], v[184:187], v[48:51]
	v_mfma_f32_16x16x32_bf16 v[32:35], v[88:91], v[192:195], v[32:35]
	v_mfma_f32_16x16x32_bf16 v[24:27], v[96:99], v[192:195], v[24:27]
	v_mfma_f32_16x16x32_bf16 v[4:7], v[88:91], v[212:215], v[4:7]
	v_mfma_f32_16x16x32_bf16 v[0:3], v[96:99], v[212:215], v[0:3]
	v_mfma_f32_16x16x32_bf16 v[68:71], v[92:95], v[180:183], v[68:71]
	v_mfma_f32_16x16x32_bf16 v[64:67], v[100:103], v[180:183], v[64:67]
	v_mfma_f32_16x16x32_bf16 v[52:55], v[92:95], v[188:191], v[52:55]
	v_mfma_f32_16x16x32_bf16 v[48:51], v[100:103], v[188:191], v[48:51]
	v_mfma_f32_16x16x32_bf16 v[32:35], v[92:95], v[196:199], v[32:35]
	v_mfma_f32_16x16x32_bf16 v[24:27], v[100:103], v[196:199], v[24:27]
	v_mfma_f32_16x16x32_bf16 v[4:7], v[92:95], v[216:219], v[4:7]
	v_mfma_f32_16x16x32_bf16 v[0:3], v[100:103], v[216:219], v[0:3]
	s_setprio 0
	s_barrier
	s_add_i32 s82, 0, 0x18000
	s_add_i32 s83, 0, 0x1c000
	v_add_u32_e32 v84, s82, v200
	v_add_u32_e32 v100, s83, v200
	ds_read_b128 v[72:75], v84
	ds_read_b128 v[76:79], v84 offset:1024
	ds_read_b128 v[80:83], v84 offset:2048
	ds_read_b128 v[84:87], v84 offset:3072
	ds_read_b128 v[88:91], v100
	ds_read_b128 v[92:95], v100 offset:1024
	ds_read_b128 v[96:99], v100 offset:2048
	ds_read_b128 v[100:103], v100 offset:3072
	s_add_u32 s76, s80, 0x20000
	s_addc_u32 s77, s81, 0
	s_mov_b32 m0, s86
	v_lshl_add_u64 v[228:229], s[76:77], 0, v[160:161]
	ds_read_b128 v[176:179], v209 offset:32768
	ds_read_b128 v[180:183], v209 offset:33792
	ds_read_b128 v[184:187], v209 offset:34816
	ds_read_b128 v[188:191], v209 offset:35840
	ds_read_b128 v[192:195], v209 offset:36864
	ds_read_b128 v[196:199], v209 offset:37888
	ds_read_b128 v[212:215], v209 offset:38912
	ds_read_b128 v[216:219], v209 offset:39936
	global_load_lds_dwordx4 v[228:229], off
	v_lshl_add_u64 v[228:229], s[76:77], 0, v[164:165]
	s_mov_b32 m0, s87
	s_nop 0
	global_load_lds_dwordx4 v[228:229], off
	s_waitcnt vmcnt(8)
	s_waitcnt lgkmcnt(0)
	s_barrier
; #define PG8_STAGE(bufoff, gbase, voff) do { _Pragma("unroll") for (int _i = 0; _i < 2; ++_i) \
;         __builtin_amdgcn_global_load_lds((const unsigned*)((const char*)(gbase) + (voff)[_i]), (PG8_LAS unsigned*)(lds + (bufoff) + ldsw + _i * 8192), 16, 0, 0); } while (0)
; #define PG8_LDA(dst, b, h) do { _Pragma("unroll") for (int m = 0; m < 4; ++m) _Pragma("unroll") for (int k = 0; k < 2; ++k) dst[m][k] = *(const PG8_LAS bf16x8*)(lds + PG8_SA(b, h) + aoff + m * 2048 + k * 1024); } while (0)
; #define PG8_MMA(ai, bj, At, Bt) do { __builtin_amdgcn_s_setprio(1); _Pragma("unroll") for (int m = 0; m < 4; ++m) _Pragma("unroll") for (int n = 0; n < 2; ++n) _Pragma("unroll") for (int k = 0; k < 2; ++k) \
;         acc[ai][bj][m][n] = __builtin_amdgcn_mfma_f32_16x16x32_bf16(Bt[n][k], At[m][k], acc[ai][bj][m][n], 0, 0, 0); __builtin_amdgcn_s_setprio(0); } while (0)
; #define PG8_WAIT_V(n) asm volatile("s_waitcnt vmcnt(" #n ")" ::: "memory")
; #define PG8_WAIT_L(n) asm volatile("s_waitcnt lgkmcnt(" #n ")" ::: "memory")
; #define PG8_BAR __builtin_amdgcn_s_barrier()
; #define PG8_SCHED __builtin_amdgcn_sched_barrier(0)
; template <class Epi, class Sched, bool ALIGN_EPI = false, bool SP2 = false, bool AROWS128 = false>
; __device__ __forceinline__ void gemm_phase(PG8_LAS unsigned char* lds, const Gemm g, const Sched& S, const Epi& E) {
;     ...
;         for (int t = 0; t < nt; t += 2) {
;     ...
;             PG8_WAIT_V(8); PG8_WAIT_L(0); PG8_BAR; PG8_MMA(0, 0, At, B0); PG8_MMA(0, 1, At, B1); PG8_BAR; PG8_SCHED;
;             PG8_LDA(At, 1, 1); PG8_STAGE(PG8_SB(1, 0), b3, voffB); PG8_STAGE(PG8_SB(1, 1), b3 + hstep, voffB); PG8_STAGE(PG8_SA(1, 0), a3, voffA);
;             PG8_WAIT_V(8); PG8_WAIT_L(0); PG8_BAR; PG8_MMA(1, 0, At, B0); PG8_MMA(1, 1, At, B1); PG8_BAR; PG8_SCHED;
	s_setprio 1
	s_waitcnt lgkmcnt(0)
	v_mfma_f32_16x16x32_bf16 v[36:39], v[72:75], v[176:179], v[36:39]
	v_mfma_f32_16x16x32_bf16 v[28:31], v[80:83], v[176:179], v[28:31]
	v_mfma_f32_16x16x32_bf16 v[140:143], v[72:75], v[184:187], v[140:143]
	v_mfma_f32_16x16x32_bf16 v[136:139], v[80:83], v[184:187], v[136:139]
	v_mfma_f32_16x16x32_bf16 v[124:127], v[72:75], v[192:195], v[124:127]
	v_mfma_f32_16x16x32_bf16 v[120:123], v[80:83], v[192:195], v[120:123]
	v_mfma_f32_16x16x32_bf16 v[108:111], v[72:75], v[212:215], v[108:111]
	v_mfma_f32_16x16x32_bf16 v[104:107], v[80:83], v[212:215], v[104:107]
	v_mfma_f32_16x16x32_bf16 v[36:39], v[76:79], v[180:183], v[36:39]
	v_mfma_f32_16x16x32_bf16 v[28:31], v[84:87], v[180:183], v[28:31]
	v_mfma_f32_16x16x32_bf16 v[140:143], v[76:79], v[188:191], v[140:143]
	v_mfma_f32_16x16x32_bf16 v[136:139], v[84:87], v[188:191], v[136:139]
	v_mfma_f32_16x16x32_bf16 v[124:127], v[76:79], v[196:199], v[124:127]
	v_mfma_f32_16x16x32_bf16 v[120:123], v[84:87], v[196:199], v[120:123]
	v_mfma_f32_16x16x32_bf16 v[108:111], v[76:79], v[216:219], v[108:111]
	v_mfma_f32_16x16x32_bf16 v[104:107], v[84:87], v[216:219], v[104:107]
	s_setprio 0
	s_setprio 1
	v_mfma_f32_16x16x32_bf16 v[156:159], v[88:91], v[176:179], v[156:159]
	v_mfma_f32_16x16x32_bf16 v[152:155], v[96:99], v[176:179], v[152:155]
	v_mfma_f32_16x16x32_bf16 v[148:151], v[88:91], v[184:187], v[148:151]
	v_mfma_f32_16x16x32_bf16 v[144:147], v[96:99], v[184:187], v[144:147]
	v_mfma_f32_16x16x32_bf16 v[132:135], v[88:91], v[192:195], v[132:135]
	v_mfma_f32_16x16x32_bf16 v[128:131], v[96:99], v[192:195], v[128:131]
	v_mfma_f32_16x16x32_bf16 v[116:119], v[88:91], v[212:215], v[116:119]
	v_mfma_f32_16x16x32_bf16 v[112:115], v[96:99], v[212:215], v[112:115]
	v_mfma_f32_16x16x32_bf16 v[156:159], v[92:95], v[180:183], v[156:159]
	v_mfma_f32_16x16x32_bf16 v[152:155], v[100:103], v[180:183], v[152:155]
	v_mfma_f32_16x16x32_bf16 v[148:151], v[92:95], v[188:191], v[148:151]
	v_mfma_f32_16x16x32_bf16 v[144:147], v[100:103], v[188:191], v[144:147]
	v_mfma_f32_16x16x32_bf16 v[132:135], v[92:95], v[196:199], v[132:135]
	v_mfma_f32_16x16x32_bf16 v[128:131], v[100:103], v[196:199], v[128:131]
	v_mfma_f32_16x16x32_bf16 v[116:119], v[92:95], v[216:219], v[116:119]
	v_mfma_f32_16x16x32_bf16 v[112:115], v[100:103], v[216:219], v[112:115]
	s_setprio 0
	s_barrier
	s_add_i32 s76, s82, s35
	v_lshl_add_u64 v[220:221], v[220:221], 0, s[26:27]
	s_mov_b32 m0, s76
	ds_read_b128 v[176:179], v209 offset:49152
	ds_read_b128 v[180:183], v209 offset:50176
	ds_read_b128 v[184:187], v209 offset:51200
	ds_read_b128 v[188:191], v209 offset:52224
	ds_read_b128 v[192:195], v209 offset:53248
	ds_read_b128 v[196:199], v209 offset:54272
	ds_read_b128 v[212:215], v209 offset:55296
	ds_read_b128 v[216:219], v209 offset:56320
	global_load_lds_dwordx4 v[220:221], off
	s_add_i32 m0, s76, 0x2000
	s_add_u32 s20, s20, 0x40080
	v_lshl_add_u64 v[220:221], v[222:223], 0, s[26:27]
	s_addc_u32 s21, s21, 0
	s_add_i32 s76, s83, s35
	global_load_lds_dwordx4 v[220:221], off
	v_lshl_add_u64 v[220:221], s[20:21], 0, v[162:163]
	s_mov_b32 m0, s76
	s_nop 0
	global_load_lds_dwordx4 v[220:221], off
	v_lshl_add_u64 v[220:221], s[20:21], 0, v[166:167]
	s_add_i32 m0, s76, 0x2000
	s_nop 0
	global_load_lds_dwordx4 v[220:221], off
	v_lshl_add_u64 v[220:221], v[224:225], 0, s[26:27]
	s_mov_b32 m0, s89
	s_nop 0
	global_load_lds_dwordx4 v[220:221], off
	v_lshl_add_u64 v[220:221], v[226:227], 0, s[26:27]
	s_mov_b32 m0, s90
	s_nop 0
	global_load_lds_dwordx4 v[220:221], off
	s_waitcnt vmcnt(8)
	s_waitcnt lgkmcnt(0)
	s_barrier
	s_setprio 1
	s_waitcnt lgkmcnt(0)
	v_mfma_f32_16x16x32_bf16 v[60:63], v[72:75], v[176:179], v[60:63]
	v_mfma_f32_16x16x32_bf16 v[56:59], v[80:83], v[176:179], v[56:59]
	v_mfma_f32_16x16x32_bf16 v[44:47], v[72:75], v[184:187], v[44:47]
	v_mfma_f32_16x16x32_bf16 v[40:43], v[80:83], v[184:187], v[40:43]
	v_mfma_f32_16x16x32_bf16 v[20:23], v[72:75], v[192:195], v[20:23]
	v_mfma_f32_16x16x32_bf16 v[16:19], v[80:83], v[192:195], v[16:19]
	v_mfma_f32_16x16x32_bf16 v[12:15], v[72:75], v[212:215], v[12:15]
	v_mfma_f32_16x16x32_bf16 v[8:11], v[80:83], v[212:215], v[8:11]
	v_mfma_f32_16x16x32_bf16 v[60:63], v[76:79], v[180:183], v[60:63]
	v_mfma_f32_16x16x32_bf16 v[56:59], v[84:87], v[180:183], v[56:59]
	v_mfma_f32_16x16x32_bf16 v[44:47], v[76:79], v[188:191], v[44:47]
	v_mfma_f32_16x16x32_bf16 v[40:43], v[84:87], v[188:191], v[40:43]
	v_mfma_f32_16x16x32_bf16 v[20:23], v[76:79], v[196:199], v[20:23]
	v_mfma_f32_16x16x32_bf16 v[16:19], v[84:87], v[196:199], v[16:19]
	v_mfma_f32_16x16x32_bf16 v[12:15], v[76:79], v[216:219], v[12:15]
	v_mfma_f32_16x16x32_bf16 v[8:11], v[84:87], v[216:219], v[8:11]
	s_setprio 0
	s_setprio 1
	v_mfma_f32_16x16x32_bf16 v[68:71], v[88:91], v[176:179], v[68:71]
	v_mfma_f32_16x16x32_bf16 v[64:67], v[96:99], v[176:179], v[64:67]
	v_mfma_f32_16x16x32_bf16 v[52:55], v[88:91], v[184:187], v[52:55]
	v_mfma_f32_16x16x32_bf16 v[48:51], v[96:99], v[184:187], v[48:51]
	v_mfma_f32_16x16x32_bf16 v[32:35], v[88:91], v[192:195], v[32:35]
	v_mfma_f32_16x16x32_bf16 v[24:27], v[96:99], v[192:195], v[24:27]
	v_mfma_f32_16x16x32_bf16 v[4:7], v[88:91], v[212:215], v[4:7]
	v_mfma_f32_16x16x32_bf16 v[0:3], v[96:99], v[212:215], v[0:3]
	v_mfma_f32_16x16x32_bf16 v[68:71], v[92:95], v[180:183], v[68:71]
	v_mfma_f32_16x16x32_bf16 v[64:67], v[100:103], v[180:183], v[64:67]
	v_mfma_f32_16x16x32_bf16 v[52:55], v[92:95], v[188:191], v[52:55]
	v_mfma_f32_16x16x32_bf16 v[48:51], v[100:103], v[188:191], v[48:51]
	v_mfma_f32_16x16x32_bf16 v[32:35], v[92:95], v[196:199], v[32:35]
	v_mfma_f32_16x16x32_bf16 v[24:27], v[100:103], v[196:199], v[24:27]
	v_mfma_f32_16x16x32_bf16 v[4:7], v[92:95], v[216:219], v[4:7]
	v_mfma_f32_16x16x32_bf16 v[0:3], v[100:103], v[216:219], v[0:3]
	s_setprio 0
	s_barrier
	s_add_i32 s73, s73, 2
	s_add_u32 s18, s18, 0x100
	s_addc_u32 s19, s19, 0
	s_add_u32 s65, s65, 0x100
	s_addc_u32 s72, s72, 0
	s_cmp_gt_u32 s73, 13
	s_cbranch_scc0 .LBB0_626
	s_nop 0
	s_and_b64 vcc, exec, s[28:29]
	s_cbranch_vccz .LBB0_629
	s_barrier

; #define PG8_STAGE(bufoff, gbase, voff) do { _Pragma("unroll") for (int _i = 0; _i < 2; ++_i) \
;         __builtin_amdgcn_global_load_lds((const unsigned*)((const char*)(gbase) + (voff)[_i]), (PG8_LAS unsigned*)(lds + (bufoff) + ldsw + _i * 8192), 16, 0, 0); } while (0)
; #define PG8_LDA(dst, b, h) do { _Pragma("unroll") for (int m = 0; m < 4; ++m) _Pragma("unroll") for (int k = 0; k < 2; ++k) dst[m][k] = *(const PG8_LAS bf16x8*)(lds + PG8_SA(b, h) + aoff + m * 2048 + k * 1024); } while (0)
; #define PG8_LDB(dst, b, h) do { _Pragma("unroll") for (int n = 0; n < 2; ++n) _Pragma("unroll") for (int k = 0; k < 2; ++k) dst[n][k] = *(const PG8_LAS bf16x8*)(lds + PG8_SB(b, h) + boff + n * 2048 + k * 1024); } while (0)
; #define PG8_WAIT_V(n) asm volatile("s_waitcnt vmcnt(" #n ")" ::: "memory")
; #define PG8_WAIT_L(n) asm volatile("s_waitcnt lgkmcnt(" #n ")" ::: "memory")
; #define PG8_BAR __builtin_amdgcn_s_barrier()
; #define PG8_SCHED __builtin_amdgcn_sched_barrier(0)
; template <class Epi, class Sched, bool ALIGN_EPI = false, bool SP2 = false, bool AROWS128 = false>
; __device__ __forceinline__ void gemm_phase(PG8_LAS unsigned char* lds, const Gemm g, const Sched& S, const Epi& E) {
;     ...
;         const char* nA = has_next ? (const char*)g.A + (size_t)nxt.pm * tstep : cA; const char* nB = has_next ? (const char*)g.Bt + (size_t)nxt.pn * tstep : cB;
;         for (int t = 0; t < nt; t += 2) {
;             const bool last = (t == nt - 2);
;             const char* a1 = cA + (size_t)(t + 1) * kstep;
;             const char* a2 = last ? nA : cA + (size_t)(t + 2) * kstep; const char* b2 = last ? nB : cB + (size_t)(t + 2) * kstep;
;             const char* a3 = a2 + kstep; const char* b3 = b2 + kstep;
;             if (last && has_next) S.a_ready(nxt);
;             if constexpr (SP2) {
;             PG8_LDB(B0, 0, 0); PG8_LDB(B1, 0, 1); PG8_SCHED; PG8_LDA(At, 0, 0); PG8_STAGE(PG8_SA(1, 1), a1 + hstepA, voffA);
;             PG8_WAIT_V(8); PG8_WAIT_L(0); PG8_BAR; PG8_MMA(0, 0, At, B0); PG8_MMA(0, 1, At, B1); PG8_BAR; PG8_SCHED;
;     ...
; #pragma unroll
;         for (int a = 0; a < 2; ++a)
; #pragma unroll
;             for (int b = 0; b < 2; ++b)
; #pragma unroll
;                 for (int m = 0; m < 4; ++m)
; #pragma unroll
;                     for (int n = 0; n < 2; ++n) acc[a][b][m][n] = (f32x4){0.f, 0.f, 0.f, 0.f};
.LBB0_751:
	s_ashr_i32 s25, s24, 31
	s_lshl_b64 s[26:27], s[24:25], 21
	s_add_u32 s26, s44, s26
	s_addc_u32 s27, s45, s27
	s_and_b64 s[28:29], s[0:1], exec
	s_cselect_b32 s25, s27, s37
	s_cselect_b32 s65, s26, s36
	s_ashr_i32 s21, s20, 31
	s_lshl_b64 s[28:29], s[20:21], 21
	v_readlane_b32 s48, v255, 13
	v_readlane_b32 s49, v255, 14
	s_add_u32 s28, s48, s28
	s_addc_u32 s29, s49, s29
	s_and_b64 s[48:49], s[0:1], exec
	s_cselect_b32 s21, s29, s39
	s_cselect_b32 s72, s28, s38
	s_add_u32 s36, s36, 0x100080
	s_addc_u32 s37, s37, 0
	s_add_u32 s73, s38, 0x100
	v_mov_b32_e32 v0, 0
	s_addc_u32 s76, s39, 0
	s_mov_b32 s77, -2
	v_mov_b64_e32 v[0:1], 0
	v_mov_b64_e32 v[2:3], 0
	v_mov_b64_e32 v[4:5], 0
	v_mov_b64_e32 v[6:7], 0
	v_mov_b64_e32 v[8:9], 0
	v_mov_b64_e32 v[10:11], 0
	v_mov_b64_e32 v[12:13], 0
	v_mov_b64_e32 v[14:15], 0
	v_mov_b64_e32 v[16:17], 0
	v_mov_b64_e32 v[18:19], 0
	v_mov_b64_e32 v[20:21], 0
	v_mov_b64_e32 v[22:23], 0
	v_mov_b64_e32 v[24:25], 0
	v_mov_b64_e32 v[26:27], 0
	v_mov_b64_e32 v[28:29], 0
	v_mov_b64_e32 v[30:31], 0
	v_mov_b64_e32 v[32:33], 0
	v_mov_b64_e32 v[34:35], 0
	v_mov_b64_e32 v[36:37], 0
	v_mov_b64_e32 v[38:39], 0
	v_mov_b64_e32 v[40:41], 0
	v_mov_b64_e32 v[42:43], 0
	v_mov_b64_e32 v[44:45], 0
	v_mov_b64_e32 v[46:47], 0
	v_mov_b64_e32 v[48:49], 0
	v_mov_b64_e32 v[50:51], 0
	v_mov_b64_e32 v[52:53], 0
	v_mov_b64_e32 v[54:55], 0
	v_mov_b64_e32 v[56:57], 0
	v_mov_b64_e32 v[58:59], 0
	v_mov_b64_e32 v[60:61], 0
	v_mov_b64_e32 v[62:63], 0
	v_mov_b64_e32 v[64:65], 0
	v_mov_b64_e32 v[66:67], 0
	v_mov_b64_e32 v[68:69], 0
	v_mov_b64_e32 v[70:71], 0
	v_mov_b64_e32 v[72:73], 0
	v_mov_b64_e32 v[74:75], 0
	v_mov_b64_e32 v[76:77], 0
	v_mov_b64_e32 v[78:79], 0
	v_mov_b64_e32 v[80:81], 0
	v_mov_b64_e32 v[82:83], 0
	v_mov_b64_e32 v[84:85], 0
	v_mov_b64_e32 v[86:87], 0
	v_mov_b64_e32 v[88:89], 0
	v_mov_b64_e32 v[90:91], 0
	v_mov_b64_e32 v[92:93], 0
	v_mov_b64_e32 v[94:95], 0
	v_mov_b64_e32 v[96:97], 0
	v_mov_b64_e32 v[98:99], 0
	v_mov_b64_e32 v[100:101], 0
	v_mov_b64_e32 v[102:103], 0
	v_mov_b64_e32 v[104:105], 0
	v_mov_b64_e32 v[106:107], 0
	v_mov_b64_e32 v[108:109], 0
	v_mov_b64_e32 v[110:111], 0
	v_mov_b64_e32 v[112:113], 0
	v_mov_b64_e32 v[114:115], 0
	v_mov_b64_e32 v[116:117], 0
	v_mov_b64_e32 v[118:119], 0
	v_mov_b64_e32 v[120:121], 0
	v_mov_b64_e32 v[122:123], 0
	v_mov_b64_e32 v[124:125], 0
	v_mov_b64_e32 v[126:127], 0
	s_nop 0
.LBB0_752:
	ds_read_b128 v[152:155], v149
	ds_read_b128 v[156:159], v149 offset:1024
	ds_read_b128 v[160:163], v149 offset:2048
	ds_read_b128 v[164:167], v149 offset:3072
	ds_read_b128 v[168:171], v150
	ds_read_b128 v[172:175], v150 offset:1024
	ds_read_b128 v[176:179], v150 offset:2048
	ds_read_b128 v[180:183], v150 offset:3072
	s_add_u32 s38, s36, 0xfff00080
	s_addc_u32 s39, s37, -1
	s_cmp_eq_u32 s77, 60
	s_cselect_b32 s49, s25, s39
	s_cselect_b32 s48, s65, s38
	s_cselect_b32 s39, s21, s76
	s_cselect_b32 s38, s72, s73
	v_lshl_add_u64 v[144:145], s[36:37], 0, v[136:137]
	s_add_i32 m0, s31, 0xc000
	ds_read_b128 v[184:187], v151
	ds_read_b128 v[188:191], v151 offset:1024
	ds_read_b128 v[192:195], v151 offset:2048
	ds_read_b128 v[196:199], v151 offset:3072
	ds_read_b128 v[200:203], v151 offset:4096
	ds_read_b128 v[204:207], v151 offset:5120
	ds_read_b128 v[212:215], v151 offset:6144
	ds_read_b128 v[216:219], v151 offset:7168
	global_load_lds_dwordx4 v[144:145], off
	v_lshl_add_u64 v[144:145], s[36:37], 0, v[138:139]
	s_add_i32 m0, s31, 0xe000
	s_nop 0
	global_load_lds_dwordx4 v[144:145], off
	s_waitcnt vmcnt(8)
	s_waitcnt lgkmcnt(0)
	s_barrier
	s_setprio 1
	s_waitcnt lgkmcnt(0)
	v_mfma_f32_16x16x32_bf16 v[124:127], v[152:155], v[184:187], v[124:127]
	v_mfma_f32_16x16x32_bf16 v[120:123], v[160:163], v[184:187], v[120:123]
	v_mfma_f32_16x16x32_bf16 v[116:119], v[152:155], v[192:195], v[116:119]
	v_mfma_f32_16x16x32_bf16 v[108:111], v[160:163], v[192:195], v[108:111]
	v_mfma_f32_16x16x32_bf16 v[100:103], v[152:155], v[200:203], v[100:103]
	v_mfma_f32_16x16x32_bf16 v[92:95], v[160:163], v[200:203], v[92:95]
	v_mfma_f32_16x16x32_bf16 v[84:87], v[152:155], v[212:215], v[84:87]
	v_mfma_f32_16x16x32_bf16 v[76:79], v[160:163], v[212:215], v[76:79]
	v_mfma_f32_16x16x32_bf16 v[124:127], v[156:159], v[188:191], v[124:127]
	v_mfma_f32_16x16x32_bf16 v[120:123], v[164:167], v[188:191], v[120:123]
	v_mfma_f32_16x16x32_bf16 v[116:119], v[156:159], v[196:199], v[116:119]
	v_mfma_f32_16x16x32_bf16 v[108:111], v[164:167], v[196:199], v[108:111]
	v_mfma_f32_16x16x32_bf16 v[100:103], v[156:159], v[204:207], v[100:103]
	v_mfma_f32_16x16x32_bf16 v[92:95], v[164:167], v[204:207], v[92:95]
	v_mfma_f32_16x16x32_bf16 v[84:87], v[156:159], v[216:219], v[84:87]
	v_mfma_f32_16x16x32_bf16 v[76:79], v[164:167], v[216:219], v[76:79]
	s_setprio 0
	s_setprio 1
	v_mfma_f32_16x16x32_bf16 v[112:115], v[168:171], v[184:187], v[112:115]
	v_mfma_f32_16x16x32_bf16 v[104:107], v[176:179], v[184:187], v[104:107]
	v_mfma_f32_16x16x32_bf16 v[96:99], v[168:171], v[192:195], v[96:99]
	v_mfma_f32_16x16x32_bf16 v[88:91], v[176:179], v[192:195], v[88:91]
	v_mfma_f32_16x16x32_bf16 v[80:83], v[168:171], v[200:203], v[80:83]
	v_mfma_f32_16x16x32_bf16 v[72:75], v[176:179], v[200:203], v[72:75]
	v_mfma_f32_16x16x32_bf16 v[68:71], v[168:171], v[212:215], v[68:71]
	v_mfma_f32_16x16x32_bf16 v[64:67], v[176:179], v[212:215], v[64:67]
	v_mfma_f32_16x16x32_bf16 v[112:115], v[172:175], v[188:191], v[112:115]
	v_mfma_f32_16x16x32_bf16 v[104:107], v[180:183], v[188:191], v[104:107]
	v_mfma_f32_16x16x32_bf16 v[96:99], v[172:175], v[196:199], v[96:99]
	v_mfma_f32_16x16x32_bf16 v[88:91], v[180:183], v[196:199], v[88:91]
	v_mfma_f32_16x16x32_bf16 v[80:83], v[172:175], v[204:207], v[80:83]
	v_mfma_f32_16x16x32_bf16 v[72:75], v[180:183], v[204:207], v[72:75]
	v_mfma_f32_16x16x32_bf16 v[68:71], v[172:175], v[216:219], v[68:71]
	v_mfma_f32_16x16x32_bf16 v[64:67], v[180:183], v[216:219], v[64:67]
	s_setprio 0
	s_barrier
; #define PG8_STAGE(bufoff, gbase, voff) do { _Pragma("unroll") for (int _i = 0; _i < 2; ++_i) \
;         __builtin_amdgcn_global_load_lds((const unsigned*)((const char*)(gbase) + (voff)[_i]), (PG8_LAS unsigned*)(lds + (bufoff) + ldsw + _i * 8192), 16, 0, 0); } while (0)
; #define PG8_LDA(dst, b, h) do { _Pragma("unroll") for (int m = 0; m < 4; ++m) _Pragma("unroll") for (int k = 0; k < 2; ++k) dst[m][k] = *(const PG8_LAS bf16x8*)(lds + PG8_SA(b, h) + aoff + m * 2048 + k * 1024); } while (0)
; #define PG8_LDB(dst, b, h) do { _Pragma("unroll") for (int n = 0; n < 2; ++n) _Pragma("unroll") for (int k = 0; k < 2; ++k) dst[n][k] = *(const PG8_LAS bf16x8*)(lds + PG8_SB(b, h) + boff + n * 2048 + k * 1024); } while (0)
; #define PG8_MMA(ai, bj, At, Bt) do { __builtin_amdgcn_s_setprio(1); _Pragma("unroll") for (int m = 0; m < 4; ++m) _Pragma("unroll") for (int n = 0; n < 2; ++n) _Pragma("unroll") for (int k = 0; k < 2; ++k) \
;         acc[ai][bj][m][n] = __builtin_amdgcn_mfma_f32_16x16x32_bf16(Bt[n][k], At[m][k], acc[ai][bj][m][n], 0, 0, 0); __builtin_amdgcn_s_setprio(0); } while (0)
; #define PG8_WAIT_V(n) asm volatile("s_waitcnt vmcnt(" #n ")" ::: "memory")
; #define PG8_WAIT_L(n) asm volatile("s_waitcnt lgkmcnt(" #n ")" ::: "memory")
; #define PG8_BAR __builtin_amdgcn_s_barrier()
; #define PG8_SCHED __builtin_amdgcn_sched_barrier(0)
; template <class Epi, class Sched, bool ALIGN_EPI = false, bool SP2 = false, bool AROWS128 = false>
; __device__ __forceinline__ void gemm_phase(PG8_LAS unsigned char* lds, const Gemm g, const Sched& S, const Epi& E) {
;     ...
;             PG8_LDA(At, 0, 1); PG8_STAGE(PG8_SB(0, 0), b2, voffB); PG8_STAGE(PG8_SB(0, 1), b2 + hstep, voffB); PG8_STAGE(PG8_SA(0, 0), a2, voffA);
;             PG8_WAIT_V(8); PG8_WAIT_L(0); PG8_BAR; PG8_MMA(1, 0, At, B0); PG8_MMA(1, 1, At, B1); PG8_BAR; PG8_SCHED;
;             PG8_LDB(B0, 1, 0); PG8_LDB(B1, 1, 1); PG8_SCHED; PG8_LDA(At, 1, 0); PG8_STAGE(PG8_SA(0, 1), a2 + hstepA, voffA);
;             PG8_WAIT_V(8); PG8_WAIT_L(0); PG8_BAR; PG8_MMA(0, 0, At, B0); PG8_MMA(0, 1, At, B1); PG8_BAR; PG8_SCHED;
	s_add_i32 s78, s58, s3
	v_lshl_add_u64 v[144:145], s[38:39], 0, v[132:133]
	s_mov_b32 m0, s78
	ds_read_b128 v[184:187], v151 offset:16384
	ds_read_b128 v[188:191], v151 offset:17408
	ds_read_b128 v[192:195], v151 offset:18432
	ds_read_b128 v[196:199], v151 offset:19456
	ds_read_b128 v[200:203], v151 offset:20480
	ds_read_b128 v[204:207], v151 offset:21504
	ds_read_b128 v[212:215], v151 offset:22528
	ds_read_b128 v[216:219], v151 offset:23552
	global_load_lds_dwordx4 v[144:145], off
	s_add_i32 m0, s78, 0x2000
	s_add_u32 s78, s38, 0x100000
	v_lshl_add_u64 v[208:209], s[38:39], 0, v[128:129]
	s_addc_u32 s79, s39, 0
	s_add_i32 s80, s59, s3
	global_load_lds_dwordx4 v[208:209], off
	v_lshl_add_u64 v[220:221], s[78:79], 0, v[132:133]
	s_mov_b32 m0, s80
	v_lshl_add_u64 v[222:223], s[48:49], 0, v[130:131]
	global_load_lds_dwordx4 v[220:221], off
	v_lshl_add_u64 v[220:221], s[78:79], 0, v[128:129]
	s_add_i32 m0, s80, 0x2000
	s_nop 0
	global_load_lds_dwordx4 v[220:221], off
	v_lshl_add_u64 v[220:221], s[48:49], 0, v[134:135]
	s_mov_b32 m0, s31
	s_nop 0
	global_load_lds_dwordx4 v[220:221], off
	s_mov_b32 m0, s50
	s_nop 0
	global_load_lds_dwordx4 v[222:223], off
	s_waitcnt vmcnt(8)
	s_waitcnt lgkmcnt(0)
	s_barrier
	s_setprio 1
	s_waitcnt lgkmcnt(0)
	v_mfma_f32_16x16x32_bf16 v[60:63], v[152:155], v[184:187], v[60:63]
	v_mfma_f32_16x16x32_bf16 v[56:59], v[160:163], v[184:187], v[56:59]
	v_mfma_f32_16x16x32_bf16 v[52:55], v[152:155], v[192:195], v[52:55]
	v_mfma_f32_16x16x32_bf16 v[44:47], v[160:163], v[192:195], v[44:47]
	v_mfma_f32_16x16x32_bf16 v[36:39], v[152:155], v[200:203], v[36:39]
	v_mfma_f32_16x16x32_bf16 v[28:31], v[160:163], v[200:203], v[28:31]
	v_mfma_f32_16x16x32_bf16 v[20:23], v[152:155], v[212:215], v[20:23]
	v_mfma_f32_16x16x32_bf16 v[12:15], v[160:163], v[212:215], v[12:15]
	v_mfma_f32_16x16x32_bf16 v[60:63], v[156:159], v[188:191], v[60:63]
	v_mfma_f32_16x16x32_bf16 v[56:59], v[164:167], v[188:191], v[56:59]
	v_mfma_f32_16x16x32_bf16 v[52:55], v[156:159], v[196:199], v[52:55]
	v_mfma_f32_16x16x32_bf16 v[44:47], v[164:167], v[196:199], v[44:47]
	v_mfma_f32_16x16x32_bf16 v[36:39], v[156:159], v[204:207], v[36:39]
	v_mfma_f32_16x16x32_bf16 v[28:31], v[164:167], v[204:207], v[28:31]
	v_mfma_f32_16x16x32_bf16 v[20:23], v[156:159], v[216:219], v[20:23]
	v_mfma_f32_16x16x32_bf16 v[12:15], v[164:167], v[216:219], v[12:15]
	s_setprio 0
	s_setprio 1
	v_mfma_f32_16x16x32_bf16 v[48:51], v[168:171], v[184:187], v[48:51]
	v_mfma_f32_16x16x32_bf16 v[40:43], v[176:179], v[184:187], v[40:43]
	v_mfma_f32_16x16x32_bf16 v[32:35], v[168:171], v[192:195], v[32:35]
	v_mfma_f32_16x16x32_bf16 v[24:27], v[176:179], v[192:195], v[24:27]
	v_mfma_f32_16x16x32_bf16 v[16:19], v[168:171], v[200:203], v[16:19]
	v_mfma_f32_16x16x32_bf16 v[8:11], v[176:179], v[200:203], v[8:11]
	v_mfma_f32_16x16x32_bf16 v[4:7], v[168:171], v[212:215], v[4:7]
	v_mfma_f32_16x16x32_bf16 v[0:3], v[176:179], v[212:215], v[0:3]
	v_mfma_f32_16x16x32_bf16 v[48:51], v[172:175], v[188:191], v[48:51]
	v_mfma_f32_16x16x32_bf16 v[40:43], v[180:183], v[188:191], v[40:43]
	v_mfma_f32_16x16x32_bf16 v[32:35], v[172:175], v[196:199], v[32:35]
	v_mfma_f32_16x16x32_bf16 v[24:27], v[180:183], v[196:199], v[24:27]
	v_mfma_f32_16x16x32_bf16 v[16:19], v[172:175], v[204:207], v[16:19]
	v_mfma_f32_16x16x32_bf16 v[8:11], v[180:183], v[204:207], v[8:11]
	v_mfma_f32_16x16x32_bf16 v[4:7], v[172:175], v[216:219], v[4:7]
	v_mfma_f32_16x16x32_bf16 v[0:3], v[180:183], v[216:219], v[0:3]
	s_setprio 0
	s_barrier
	s_add_i32 s78, 0, 0x18000
	s_add_i32 s79, 0, 0x1c000
	v_add_u32_e32 v164, s78, v147
	v_add_u32_e32 v180, s79, v147
	ds_read_b128 v[152:155], v164
	ds_read_b128 v[156:159], v164 offset:1024
	ds_read_b128 v[160:163], v164 offset:2048
	ds_read_b128 v[164:167], v164 offset:3072
	ds_read_b128 v[168:171], v180
	ds_read_b128 v[172:175], v180 offset:1024
	ds_read_b128 v[176:179], v180 offset:2048
	ds_read_b128 v[180:183], v180 offset:3072
	s_add_u32 s48, s48, 0x100000
	s_addc_u32 s49, s49, 0
	s_mov_b32 m0, s51
	v_lshl_add_u64 v[224:225], s[48:49], 0, v[134:135]
	ds_read_b128 v[184:187], v151 offset:32768
	ds_read_b128 v[188:191], v151 offset:33792
	ds_read_b128 v[192:195], v151 offset:34816
	ds_read_b128 v[196:199], v151 offset:35840
	ds_read_b128 v[200:203], v151 offset:36864
	ds_read_b128 v[204:207], v151 offset:37888
	ds_read_b128 v[212:215], v151 offset:38912
	ds_read_b128 v[216:219], v151 offset:39936
	global_load_lds_dwordx4 v[224:225], off
	v_lshl_add_u64 v[224:225], s[48:49], 0, v[130:131]
	s_mov_b32 m0, s52
	s_nop 0
	global_load_lds_dwordx4 v[224:225], off
	s_waitcnt vmcnt(8)
	s_waitcnt lgkmcnt(0)
	s_barrier
; #define PG8_STAGE(bufoff, gbase, voff) do { _Pragma("unroll") for (int _i = 0; _i < 2; ++_i) \
;         __builtin_amdgcn_global_load_lds((const unsigned*)((const char*)(gbase) + (voff)[_i]), (PG8_LAS unsigned*)(lds + (bufoff) + ldsw + _i * 8192), 16, 0, 0); } while (0)
; #define PG8_LDA(dst, b, h) do { _Pragma("unroll") for (int m = 0; m < 4; ++m) _Pragma("unroll") for (int k = 0; k < 2; ++k) dst[m][k] = *(const PG8_LAS bf16x8*)(lds + PG8_SA(b, h) + aoff + m * 2048 + k * 1024); } while (0)
; #define PG8_MMA(ai, bj, At, Bt) do { __builtin_amdgcn_s_setprio(1); _Pragma("unroll") for (int m = 0; m < 4; ++m) _Pragma("unroll") for (int n = 0; n < 2; ++n) _Pragma("unroll") for (int k = 0; k < 2; ++k) \
;         acc[ai][bj][m][n] = __builtin_amdgcn_mfma_f32_16x16x32_bf16(Bt[n][k], At[m][k], acc[ai][bj][m][n], 0, 0, 0); __builtin_amdgcn_s_setprio(0); } while (0)
; #define PG8_WAIT_V(n) asm volatile("s_waitcnt vmcnt(" #n ")" ::: "memory")
; #define PG8_WAIT_L(n) asm volatile("s_waitcnt lgkmcnt(" #n ")" ::: "memory")
; #define PG8_BAR __builtin_amdgcn_s_barrier()
; #define PG8_SCHED __builtin_amdgcn_sched_barrier(0)
; template <class Epi, class Sched, bool ALIGN_EPI = false, bool SP2 = false, bool AROWS128 = false>
; __device__ __forceinline__ void gemm_phase(PG8_LAS unsigned char* lds, const Gemm g, const Sched& S, const Epi& E) {
;     ...
;         for (int t = 0; t < nt; t += 2) {
;     ...
;             PG8_WAIT_V(8); PG8_WAIT_L(0); PG8_BAR; PG8_MMA(0, 0, At, B0); PG8_MMA(0, 1, At, B1); PG8_BAR; PG8_SCHED;
;             PG8_LDA(At, 1, 1); PG8_STAGE(PG8_SB(1, 0), b3, voffB); PG8_STAGE(PG8_SB(1, 1), b3 + hstep, voffB); PG8_STAGE(PG8_SA(1, 0), a3, voffA);
;             PG8_WAIT_V(8); PG8_WAIT_L(0); PG8_BAR; PG8_MMA(1, 0, At, B0); PG8_MMA(1, 1, At, B1); PG8_BAR; PG8_SCHED;
	s_setprio 1
	s_waitcnt lgkmcnt(0)
	v_mfma_f32_16x16x32_bf16 v[124:127], v[152:155], v[184:187], v[124:127]
	v_mfma_f32_16x16x32_bf16 v[120:123], v[160:163], v[184:187], v[120:123]
	v_mfma_f32_16x16x32_bf16 v[116:119], v[152:155], v[192:195], v[116:119]
	v_mfma_f32_16x16x32_bf16 v[108:111], v[160:163], v[192:195], v[108:111]
	v_mfma_f32_16x16x32_bf16 v[100:103], v[152:155], v[200:203], v[100:103]
	v_mfma_f32_16x16x32_bf16 v[92:95], v[160:163], v[200:203], v[92:95]
	v_mfma_f32_16x16x32_bf16 v[84:87], v[152:155], v[212:215], v[84:87]
	v_mfma_f32_16x16x32_bf16 v[76:79], v[160:163], v[212:215], v[76:79]
	v_mfma_f32_16x16x32_bf16 v[124:127], v[156:159], v[188:191], v[124:127]
	v_mfma_f32_16x16x32_bf16 v[120:123], v[164:167], v[188:191], v[120:123]
	v_mfma_f32_16x16x32_bf16 v[116:119], v[156:159], v[196:199], v[116:119]
	v_mfma_f32_16x16x32_bf16 v[108:111], v[164:167], v[196:199], v[108:111]
	v_mfma_f32_16x16x32_bf16 v[100:103], v[156:159], v[204:207], v[100:103]
	v_mfma_f32_16x16x32_bf16 v[92:95], v[164:167], v[204:207], v[92:95]
	v_mfma_f32_16x16x32_bf16 v[84:87], v[156:159], v[216:219], v[84:87]
	v_mfma_f32_16x16x32_bf16 v[76:79], v[164:167], v[216:219], v[76:79]
	s_setprio 0
	s_setprio 1
	v_mfma_f32_16x16x32_bf16 v[112:115], v[168:171], v[184:187], v[112:115]
	v_mfma_f32_16x16x32_bf16 v[104:107], v[176:179], v[184:187], v[104:107]
	v_mfma_f32_16x16x32_bf16 v[96:99], v[168:171], v[192:195], v[96:99]
	v_mfma_f32_16x16x32_bf16 v[88:91], v[176:179], v[192:195], v[88:91]
	v_mfma_f32_16x16x32_bf16 v[80:83], v[168:171], v[200:203], v[80:83]
	v_mfma_f32_16x16x32_bf16 v[72:75], v[176:179], v[200:203], v[72:75]
	v_mfma_f32_16x16x32_bf16 v[68:71], v[168:171], v[212:215], v[68:71]
	v_mfma_f32_16x16x32_bf16 v[64:67], v[176:179], v[212:215], v[64:67]
	v_mfma_f32_16x16x32_bf16 v[112:115], v[172:175], v[188:191], v[112:115]
	v_mfma_f32_16x16x32_bf16 v[104:107], v[180:183], v[188:191], v[104:107]
	v_mfma_f32_16x16x32_bf16 v[96:99], v[172:175], v[196:199], v[96:99]
	v_mfma_f32_16x16x32_bf16 v[88:91], v[180:183], v[196:199], v[88:91]
	v_mfma_f32_16x16x32_bf16 v[80:83], v[172:175], v[204:207], v[80:83]
	v_mfma_f32_16x16x32_bf16 v[72:75], v[180:183], v[204:207], v[72:75]
	v_mfma_f32_16x16x32_bf16 v[68:71], v[172:175], v[216:219], v[68:71]
	v_mfma_f32_16x16x32_bf16 v[64:67], v[180:183], v[216:219], v[64:67]
	s_setprio 0
	s_barrier
	s_add_i32 s48, s78, s3
	v_lshl_add_u64 v[144:145], v[144:145], 0, s[8:9]
	s_mov_b32 m0, s48
	ds_read_b128 v[184:187], v151 offset:49152
	ds_read_b128 v[188:191], v151 offset:50176
	ds_read_b128 v[192:195], v151 offset:51200
	ds_read_b128 v[196:199], v151 offset:52224
	ds_read_b128 v[200:203], v151 offset:53248
	ds_read_b128 v[204:207], v151 offset:54272
	ds_read_b128 v[212:215], v151 offset:55296
	ds_read_b128 v[216:219], v151 offset:56320
	global_load_lds_dwordx4 v[144:145], off
	s_add_i32 m0, s48, 0x2000
	s_add_u32 s38, s38, 0x100080
	v_lshl_add_u64 v[144:145], v[208:209], 0, s[8:9]
	s_addc_u32 s39, s39, 0
	s_add_i32 s48, s79, s3
	global_load_lds_dwordx4 v[144:145], off
	v_lshl_add_u64 v[144:145], s[38:39], 0, v[132:133]
	s_mov_b32 m0, s48
	s_nop 0
	global_load_lds_dwordx4 v[144:145], off
	v_lshl_add_u64 v[144:145], s[38:39], 0, v[128:129]
	s_add_i32 m0, s48, 0x2000
	s_nop 0
	global_load_lds_dwordx4 v[144:145], off
	v_lshl_add_u64 v[144:145], v[220:221], 0, s[8:9]
	s_mov_b32 m0, s54
	s_nop 0
	global_load_lds_dwordx4 v[144:145], off
	v_lshl_add_u64 v[144:145], v[222:223], 0, s[8:9]
	s_mov_b32 m0, s55
	s_nop 0
	global_load_lds_dwordx4 v[144:145], off
	s_waitcnt vmcnt(8)
	s_waitcnt lgkmcnt(0)
	s_barrier
	s_setprio 1
	s_waitcnt lgkmcnt(0)
	v_mfma_f32_16x16x32_bf16 v[60:63], v[152:155], v[184:187], v[60:63]
	v_mfma_f32_16x16x32_bf16 v[56:59], v[160:163], v[184:187], v[56:59]
	v_mfma_f32_16x16x32_bf16 v[52:55], v[152:155], v[192:195], v[52:55]
	v_mfma_f32_16x16x32_bf16 v[44:47], v[160:163], v[192:195], v[44:47]
	v_mfma_f32_16x16x32_bf16 v[36:39], v[152:155], v[200:203], v[36:39]
	v_mfma_f32_16x16x32_bf16 v[28:31], v[160:163], v[200:203], v[28:31]
	v_mfma_f32_16x16x32_bf16 v[20:23], v[152:155], v[212:215], v[20:23]
	v_mfma_f32_16x16x32_bf16 v[12:15], v[160:163], v[212:215], v[12:15]
	v_mfma_f32_16x16x32_bf16 v[60:63], v[156:159], v[188:191], v[60:63]
	v_mfma_f32_16x16x32_bf16 v[56:59], v[164:167], v[188:191], v[56:59]
	v_mfma_f32_16x16x32_bf16 v[52:55], v[156:159], v[196:199], v[52:55]
	v_mfma_f32_16x16x32_bf16 v[44:47], v[164:167], v[196:199], v[44:47]
	v_mfma_f32_16x16x32_bf16 v[36:39], v[156:159], v[204:207], v[36:39]
	v_mfma_f32_16x16x32_bf16 v[28:31], v[164:167], v[204:207], v[28:31]
	v_mfma_f32_16x16x32_bf16 v[20:23], v[156:159], v[216:219], v[20:23]
	v_mfma_f32_16x16x32_bf16 v[12:15], v[164:167], v[216:219], v[12:15]
	s_setprio 0
	s_setprio 1
	v_mfma_f32_16x16x32_bf16 v[48:51], v[168:171], v[184:187], v[48:51]
	v_mfma_f32_16x16x32_bf16 v[40:43], v[176:179], v[184:187], v[40:43]
	v_mfma_f32_16x16x32_bf16 v[32:35], v[168:171], v[192:195], v[32:35]
	v_mfma_f32_16x16x32_bf16 v[24:27], v[176:179], v[192:195], v[24:27]
	v_mfma_f32_16x16x32_bf16 v[16:19], v[168:171], v[200:203], v[16:19]
	v_mfma_f32_16x16x32_bf16 v[8:11], v[176:179], v[200:203], v[8:11]
	v_mfma_f32_16x16x32_bf16 v[4:7], v[168:171], v[212:215], v[4:7]
	v_mfma_f32_16x16x32_bf16 v[0:3], v[176:179], v[212:215], v[0:3]
	v_mfma_f32_16x16x32_bf16 v[48:51], v[172:175], v[188:191], v[48:51]
	v_mfma_f32_16x16x32_bf16 v[40:43], v[180:183], v[188:191], v[40:43]
	v_mfma_f32_16x16x32_bf16 v[32:35], v[172:175], v[196:199], v[32:35]
	v_mfma_f32_16x16x32_bf16 v[24:27], v[180:183], v[196:199], v[24:27]
	v_mfma_f32_16x16x32_bf16 v[16:19], v[172:175], v[204:207], v[16:19]
	v_mfma_f32_16x16x32_bf16 v[8:11], v[180:183], v[204:207], v[8:11]
	v_mfma_f32_16x16x32_bf16 v[4:7], v[172:175], v[216:219], v[4:7]
	v_mfma_f32_16x16x32_bf16 v[0:3], v[180:183], v[216:219], v[0:3]
	s_setprio 0
	s_barrier
	s_add_i32 s77, s77, 2
	s_add_u32 s36, s36, 0x100
	s_addc_u32 s37, s37, 0
	s_add_u32 s73, s73, 0x100
	s_addc_u32 s76, s76, 0
	s_cmp_gt_u32 s77, 61
	s_cbranch_scc0 .LBB0_752
	s_nop 0
	s_and_b64 vcc, exec, s[10:11]
	s_cbranch_vccz .LBB0_755
	s_barrier
